# hoist serialized epilogue loads in P1/P4/P5/P6 GEMM epilogues; attention early-exit flag reads as 2x ds_read_b128 instead of 8 serialized ds_read_b32
# speedup vs baseline: 1.0119x; 1.0060x over previous
; DI unsigned pk2(float lo, float hi) { f32x2_t v = {lo, hi}; bf16x2_t b = __builtin_convertvector(v, bf16x2_t); return __builtin_bit_cast(unsigned, b); }
;     DI void operator()(const f32x4 (&acc)[2][2][4][2], const pg8::Unit& u, int wr, int wc, int fr, int fq) const {
;     ...
;         for (int ai = 0; ai < 2; ++ai)
; #pragma unroll
;             for (int m = 0; m < 4; ++m) {
;                 const int row = u.pm * 256 + ai * 128 + wr * 64 + m * 16 + fr;
;                 const float rs = rsqrtf(ss[row] * (1.0f / DM) + EPS);
;                 if (u.pn < 16) {
; #pragma unroll
;                     for (int bj = 0; bj < 2; ++bj) {
;                         const int slot = 2 * u.pn + bj;
;                         bf16* dst = heads + ((size_t)slot * M + row) * HD + wc * 32 + 8 * fq;
;                         const f32x4 a = acc[ai][bj][m][0] * rs, b = acc[ai][bj][m][1] * rs;
;                         u32x4 w; w.x = pk2(a[0], a[1]); w.y = pk2(a[2], a[3]); w.z = pk2(b[0], b[1]); w.w = pk2(b[2], b[3]);
;                         *(u32x4*)dst = w;
;                     }
;                 } else if (wc == 0) {
;                     float* dst = scal + (size_t)row * 32 + 8 * fq;
;                     *(f32x4*)dst = acc[ai][0][m][0] * rs; *(f32x4*)(dst + 4) = acc[ai][0][m][1] * rs;
;                 }
.LBB0_136:
	v_readlane_b32 s28, v254, 54
	v_readlane_b32 s29, v254, 55
	s_andn2_b64 vcc, exec, s[2:3]
	s_cbranch_vccnz .LBB0_185
	s_lshl_b32 s23, s4, 8
	v_add_u32_e32 v130, s23, v180
	v_ashrrev_i32_e32 v131, 31, v130
	v_lshl_add_u64 v[132:133], v[130:131], 2, s[14:15]
	flat_load_dword v196, v[132:133] offset:64
	flat_load_dword v197, v[132:133] offset:128
	flat_load_dword v198, v[132:133] offset:192
	flat_load_dword v199, v[132:133] offset:512
	flat_load_dword v200, v[132:133] offset:576
	flat_load_dword v201, v[132:133] offset:640
	flat_load_dword v202, v[132:133] offset:704
	flat_load_dword v132, v[132:133]
	s_cmp_gt_i32 s10, 15
	s_cselect_b64 s[26:27], -1, 0
	s_mov_b64 s[4:5], -1
	s_waitcnt vmcnt(0) lgkmcnt(0)
	v_fmamk_f32 v132, v132, 0x3a000000, v188
	v_cmp_gt_f32_e32 vcc, s57, v132
	v_mul_f32_e32 v133, 0x4b800000, v132
	s_nop 0
	v_cndmask_b32_e32 v132, v132, v133, vcc
	v_rsq_f32_e32 v132, v132
	s_nop 0
	v_mul_f32_e32 v133, 0x45800000, v132
	v_cndmask_b32_e32 v134, v132, v133, vcc
	v_cndmask_b32_e64 v132, 0, 1, s[20:21]
	s_and_b64 vcc, exec, s[26:27]
	v_cmp_ne_u32_e64 s[2:3], 1, v132
	s_cbranch_vccz .LBB0_141
	s_and_b64 vcc, exec, s[2:3]
	s_cbranch_vccnz .LBB0_140
	v_lshlrev_b64 v[132:133], 7, v[130:131]
	v_lshl_add_u64 v[132:133], v[156:157], 0, v[132:133]
	v_pk_mul_f32 v[164:165], v[128:129], v[134:135] op_sel_hi:[1,0]
	v_pk_mul_f32 v[162:163], v[126:127], v[134:135] op_sel_hi:[1,0]
	v_pk_mul_f32 v[138:139], v[124:125], v[134:135] op_sel_hi:[1,0]
	v_pk_mul_f32 v[136:137], v[122:123], v[134:135] op_sel_hi:[1,0]
	flat_store_dwordx4 v[132:133], v[162:165]
	flat_store_dwordx4 v[132:133], v[136:139] offset:16

; DI unsigned pk2(float lo, float hi) { f32x2_t v = {lo, hi}; bf16x2_t b = __builtin_convertvector(v, bf16x2_t); return __builtin_bit_cast(unsigned, b); }
;     DI void operator()(const f32x4 (&acc)[2][2][4][2], const pg8::Unit& u, int wr, int wc, int fr, int fq) const {
;     ...
;             for (int m = 0; m < 4; ++m) {
;                 const int row = u.pm * 256 + ai * 128 + wr * 64 + m * 16 + fr;
;                 const float rs = rsqrtf(ss[row] * (1.0f / DM) + EPS);
;                 if (u.pn < 16) {
; #pragma unroll
;                     for (int bj = 0; bj < 2; ++bj) {
;                         const int slot = 2 * u.pn + bj;
;                         bf16* dst = heads + ((size_t)slot * M + row) * HD + wc * 32 + 8 * fq;
;                         const f32x4 a = acc[ai][bj][m][0] * rs, b = acc[ai][bj][m][1] * rs;
;                         u32x4 w; w.x = pk2(a[0], a[1]); w.y = pk2(a[2], a[3]); w.z = pk2(b[0], b[1]); w.w = pk2(b[2], b[3]);
;                         *(u32x4*)dst = w;
;                     }
;                 } else if (wc == 0) {
;                     float* dst = scal + (size_t)row * 32 + 8 * fq;
;                     *(f32x4*)dst = acc[ai][0][m][0] * rs; *(f32x4*)(dst + 4) = acc[ai][0][m][1] * rs;
;                 }
.LBB0_143:
	s_nop 1
	v_add_u32_e32 v116, s23, v182
	v_ashrrev_i32_e32 v117, 31, v116
	v_lshl_add_u64 v[114:115], v[116:117], 2, s[14:15]
	s_andn2_b64 vcc, exec, s[26:27]
	v_fmamk_f32 v114, v196, 0x3a000000, v188
	v_mul_f32_e32 v115, 0x4b800000, v114
	v_cmp_gt_f32_e64 s[6:7], s57, v114
	s_nop 1
	v_cndmask_b32_e64 v114, v114, v115, s[6:7]
	v_rsq_f32_e32 v114, v114
	v_cndmask_b32_e64 v115, 0, 1, s[26:27]
	v_cmp_ne_u32_e64 s[4:5], 1, v115
	v_mul_f32_e32 v115, 0x45800000, v114
	v_cndmask_b32_e64 v114, v114, v115, s[6:7]
	s_mov_b64 s[6:7], -1
	s_cbranch_vccnz .LBB0_147
	s_and_b64 vcc, exec, s[2:3]
	s_cbranch_vccnz .LBB0_146
	v_lshlrev_b64 v[118:119], 7, v[116:117]
	v_lshl_add_u64 v[126:127], v[156:157], 0, v[118:119]
	v_pk_mul_f32 v[124:125], v[112:113], v[114:115] op_sel_hi:[1,0]
	v_pk_mul_f32 v[122:123], v[110:111], v[114:115] op_sel_hi:[1,0]
	v_pk_mul_f32 v[120:121], v[108:109], v[114:115] op_sel_hi:[1,0]
	v_pk_mul_f32 v[118:119], v[106:107], v[114:115] op_sel_hi:[1,0]
	flat_store_dwordx4 v[126:127], v[122:125]
	flat_store_dwordx4 v[126:127], v[118:121] offset:16

; DI unsigned pk2(float lo, float hi) { f32x2_t v = {lo, hi}; bf16x2_t b = __builtin_convertvector(v, bf16x2_t); return __builtin_bit_cast(unsigned, b); }
;     DI void operator()(const f32x4 (&acc)[2][2][4][2], const pg8::Unit& u, int wr, int wc, int fr, int fq) const {
;     ...
;             for (int m = 0; m < 4; ++m) {
;                 const int row = u.pm * 256 + ai * 128 + wr * 64 + m * 16 + fr;
;                 const float rs = rsqrtf(ss[row] * (1.0f / DM) + EPS);
;                 if (u.pn < 16) {
; #pragma unroll
;                     for (int bj = 0; bj < 2; ++bj) {
;                         const int slot = 2 * u.pn + bj;
;                         bf16* dst = heads + ((size_t)slot * M + row) * HD + wc * 32 + 8 * fq;
;                         const f32x4 a = acc[ai][bj][m][0] * rs, b = acc[ai][bj][m][1] * rs;
;                         u32x4 w; w.x = pk2(a[0], a[1]); w.y = pk2(a[2], a[3]); w.z = pk2(b[0], b[1]); w.w = pk2(b[2], b[3]);
;                         *(u32x4*)dst = w;
;                     }
;                 } else if (wc == 0) {
;                     float* dst = scal + (size_t)row * 32 + 8 * fq;
;                     *(f32x4*)dst = acc[ai][0][m][0] * rs; *(f32x4*)(dst + 4) = acc[ai][0][m][1] * rs;
;                 }
.LBB0_149:
	s_nop 1
	v_add_u32_e32 v100, s23, v183
	v_ashrrev_i32_e32 v101, 31, v100
	v_lshl_add_u64 v[98:99], v[100:101], 2, s[14:15]
	s_and_b64 vcc, exec, s[4:5]
	v_fmamk_f32 v98, v197, 0x3a000000, v188
	v_mul_f32_e32 v99, 0x4b800000, v98
	v_cmp_gt_f32_e64 s[6:7], s57, v98
	s_nop 1
	v_cndmask_b32_e64 v98, v98, v99, s[6:7]
	v_rsq_f32_e32 v98, v98
	s_nop 0
	v_mul_f32_e32 v99, 0x45800000, v98
	v_cndmask_b32_e64 v98, v98, v99, s[6:7]
	s_mov_b64 s[6:7], -1
	s_cbranch_vccnz .LBB0_153
	s_and_b64 vcc, exec, s[2:3]
	s_cbranch_vccnz .LBB0_152
	v_lshlrev_b64 v[102:103], 7, v[100:101]
	v_lshl_add_u64 v[110:111], v[156:157], 0, v[102:103]
	v_pk_mul_f32 v[108:109], v[96:97], v[98:99] op_sel_hi:[1,0]
	v_pk_mul_f32 v[106:107], v[94:95], v[98:99] op_sel_hi:[1,0]
	v_pk_mul_f32 v[104:105], v[92:93], v[98:99] op_sel_hi:[1,0]
	v_pk_mul_f32 v[102:103], v[90:91], v[98:99] op_sel_hi:[1,0]
	flat_store_dwordx4 v[110:111], v[106:109]
	flat_store_dwordx4 v[110:111], v[102:105] offset:16

; DI unsigned pk2(float lo, float hi) { f32x2_t v = {lo, hi}; bf16x2_t b = __builtin_convertvector(v, bf16x2_t); return __builtin_bit_cast(unsigned, b); }
;     DI void operator()(const f32x4 (&acc)[2][2][4][2], const pg8::Unit& u, int wr, int wc, int fr, int fq) const {
;     ...
;             for (int m = 0; m < 4; ++m) {
;                 const int row = u.pm * 256 + ai * 128 + wr * 64 + m * 16 + fr;
;                 const float rs = rsqrtf(ss[row] * (1.0f / DM) + EPS);
;                 if (u.pn < 16) {
; #pragma unroll
;                     for (int bj = 0; bj < 2; ++bj) {
;                         const int slot = 2 * u.pn + bj;
;                         bf16* dst = heads + ((size_t)slot * M + row) * HD + wc * 32 + 8 * fq;
;                         const f32x4 a = acc[ai][bj][m][0] * rs, b = acc[ai][bj][m][1] * rs;
;                         u32x4 w; w.x = pk2(a[0], a[1]); w.y = pk2(a[2], a[3]); w.z = pk2(b[0], b[1]); w.w = pk2(b[2], b[3]);
;                         *(u32x4*)dst = w;
;                     }
;                 } else if (wc == 0) {
;                     float* dst = scal + (size_t)row * 32 + 8 * fq;
;                     *(f32x4*)dst = acc[ai][0][m][0] * rs; *(f32x4*)(dst + 4) = acc[ai][0][m][1] * rs;
;                 }
.LBB0_155:
	s_nop 1
	v_add_u32_e32 v84, s23, v184
	v_ashrrev_i32_e32 v85, 31, v84
	v_lshl_add_u64 v[82:83], v[84:85], 2, s[14:15]
	s_and_b64 vcc, exec, s[4:5]
	v_fmamk_f32 v82, v198, 0x3a000000, v188
	v_mul_f32_e32 v83, 0x4b800000, v82
	v_cmp_gt_f32_e64 s[6:7], s57, v82
	s_nop 1
	v_cndmask_b32_e64 v82, v82, v83, s[6:7]
	v_rsq_f32_e32 v82, v82
	s_nop 0
	v_mul_f32_e32 v83, 0x45800000, v82
	v_cndmask_b32_e64 v82, v82, v83, s[6:7]
	s_mov_b64 s[6:7], -1
	s_cbranch_vccnz .LBB0_159
	s_and_b64 vcc, exec, s[2:3]
	s_cbranch_vccnz .LBB0_158
	v_lshlrev_b64 v[86:87], 7, v[84:85]
	v_lshl_add_u64 v[94:95], v[156:157], 0, v[86:87]
	v_pk_mul_f32 v[92:93], v[80:81], v[82:83] op_sel_hi:[1,0]
	v_pk_mul_f32 v[90:91], v[78:79], v[82:83] op_sel_hi:[1,0]
	v_pk_mul_f32 v[88:89], v[76:77], v[82:83] op_sel_hi:[1,0]
	v_pk_mul_f32 v[86:87], v[74:75], v[82:83] op_sel_hi:[1,0]
	flat_store_dwordx4 v[94:95], v[90:93]
	flat_store_dwordx4 v[94:95], v[86:89] offset:16

; DI unsigned pk2(float lo, float hi) { f32x2_t v = {lo, hi}; bf16x2_t b = __builtin_convertvector(v, bf16x2_t); return __builtin_bit_cast(unsigned, b); }
;     DI void operator()(const f32x4 (&acc)[2][2][4][2], const pg8::Unit& u, int wr, int wc, int fr, int fq) const {
;     ...
;             for (int m = 0; m < 4; ++m) {
;                 const int row = u.pm * 256 + ai * 128 + wr * 64 + m * 16 + fr;
;                 const float rs = rsqrtf(ss[row] * (1.0f / DM) + EPS);
;                 if (u.pn < 16) {
; #pragma unroll
;                     for (int bj = 0; bj < 2; ++bj) {
;                         const int slot = 2 * u.pn + bj;
;                         bf16* dst = heads + ((size_t)slot * M + row) * HD + wc * 32 + 8 * fq;
;                         const f32x4 a = acc[ai][bj][m][0] * rs, b = acc[ai][bj][m][1] * rs;
;                         u32x4 w; w.x = pk2(a[0], a[1]); w.y = pk2(a[2], a[3]); w.z = pk2(b[0], b[1]); w.w = pk2(b[2], b[3]);
;                         *(u32x4*)dst = w;
;                     }
;                 } else if (wc == 0) {
;                     float* dst = scal + (size_t)row * 32 + 8 * fq;
;                     *(f32x4*)dst = acc[ai][0][m][0] * rs; *(f32x4*)(dst + 4) = acc[ai][0][m][1] * rs;
;                 }
.LBB0_161:
	s_nop 1
	v_add_u32_e32 v68, 0x80, v130
	v_ashrrev_i32_e32 v69, 31, v68
	v_lshl_add_u64 v[66:67], v[68:69], 2, s[14:15]
	s_and_b64 vcc, exec, s[4:5]
	v_fmamk_f32 v66, v199, 0x3a000000, v188
	v_mul_f32_e32 v67, 0x4b800000, v66
	v_cmp_gt_f32_e64 s[6:7], s57, v66
	s_nop 1
	v_cndmask_b32_e64 v66, v66, v67, s[6:7]
	v_rsq_f32_e32 v66, v66
	s_nop 0
	v_mul_f32_e32 v67, 0x45800000, v66
	v_cndmask_b32_e64 v66, v66, v67, s[6:7]
	s_mov_b64 s[6:7], -1
	s_cbranch_vccnz .LBB0_165
	s_and_b64 vcc, exec, s[2:3]
	s_cbranch_vccnz .LBB0_164
	v_lshlrev_b64 v[70:71], 7, v[68:69]
	v_lshl_add_u64 v[78:79], v[156:157], 0, v[70:71]
	v_pk_mul_f32 v[76:77], v[64:65], v[66:67] op_sel_hi:[1,0]
	v_pk_mul_f32 v[74:75], v[62:63], v[66:67] op_sel_hi:[1,0]
	v_pk_mul_f32 v[72:73], v[60:61], v[66:67] op_sel_hi:[1,0]
	v_pk_mul_f32 v[70:71], v[58:59], v[66:67] op_sel_hi:[1,0]
	flat_store_dwordx4 v[78:79], v[74:77]
	flat_store_dwordx4 v[78:79], v[70:73] offset:16

; DI unsigned pk2(float lo, float hi) { f32x2_t v = {lo, hi}; bf16x2_t b = __builtin_convertvector(v, bf16x2_t); return __builtin_bit_cast(unsigned, b); }
;     DI void operator()(const f32x4 (&acc)[2][2][4][2], const pg8::Unit& u, int wr, int wc, int fr, int fq) const {
;     ...
;             for (int m = 0; m < 4; ++m) {
;                 const int row = u.pm * 256 + ai * 128 + wr * 64 + m * 16 + fr;
;                 const float rs = rsqrtf(ss[row] * (1.0f / DM) + EPS);
;                 if (u.pn < 16) {
; #pragma unroll
;                     for (int bj = 0; bj < 2; ++bj) {
;                         const int slot = 2 * u.pn + bj;
;                         bf16* dst = heads + ((size_t)slot * M + row) * HD + wc * 32 + 8 * fq;
;                         const f32x4 a = acc[ai][bj][m][0] * rs, b = acc[ai][bj][m][1] * rs;
;                         u32x4 w; w.x = pk2(a[0], a[1]); w.y = pk2(a[2], a[3]); w.z = pk2(b[0], b[1]); w.w = pk2(b[2], b[3]);
;                         *(u32x4*)dst = w;
;                     }
;                 } else if (wc == 0) {
;                     float* dst = scal + (size_t)row * 32 + 8 * fq;
;                     *(f32x4*)dst = acc[ai][0][m][0] * rs; *(f32x4*)(dst + 4) = acc[ai][0][m][1] * rs;
;                 }
.LBB0_167:
	s_nop 1
	v_add_u32_e32 v52, 0x90, v130
	v_ashrrev_i32_e32 v53, 31, v52
	v_lshl_add_u64 v[50:51], v[52:53], 2, s[14:15]
	s_and_b64 vcc, exec, s[4:5]
	v_fmamk_f32 v50, v200, 0x3a000000, v188
	v_mul_f32_e32 v51, 0x4b800000, v50
	v_cmp_gt_f32_e64 s[6:7], s57, v50
	s_nop 1
	v_cndmask_b32_e64 v50, v50, v51, s[6:7]
	v_rsq_f32_e32 v50, v50
	s_nop 0
	v_mul_f32_e32 v51, 0x45800000, v50
	v_cndmask_b32_e64 v50, v50, v51, s[6:7]
	s_mov_b64 s[6:7], -1
	s_cbranch_vccnz .LBB0_171
	s_and_b64 vcc, exec, s[2:3]
	s_cbranch_vccnz .LBB0_170
	v_lshlrev_b64 v[54:55], 7, v[52:53]
	v_lshl_add_u64 v[62:63], v[156:157], 0, v[54:55]
	v_pk_mul_f32 v[60:61], v[48:49], v[50:51] op_sel_hi:[1,0]
	v_pk_mul_f32 v[58:59], v[46:47], v[50:51] op_sel_hi:[1,0]
	v_pk_mul_f32 v[56:57], v[44:45], v[50:51] op_sel_hi:[1,0]
	v_pk_mul_f32 v[54:55], v[42:43], v[50:51] op_sel_hi:[1,0]
	flat_store_dwordx4 v[62:63], v[58:61]
	flat_store_dwordx4 v[62:63], v[54:57] offset:16

; DI unsigned pk2(float lo, float hi) { f32x2_t v = {lo, hi}; bf16x2_t b = __builtin_convertvector(v, bf16x2_t); return __builtin_bit_cast(unsigned, b); }
;     DI void operator()(const f32x4 (&acc)[2][2][4][2], const pg8::Unit& u, int wr, int wc, int fr, int fq) const {
;     ...
;             for (int m = 0; m < 4; ++m) {
;                 const int row = u.pm * 256 + ai * 128 + wr * 64 + m * 16 + fr;
;                 const float rs = rsqrtf(ss[row] * (1.0f / DM) + EPS);
;                 if (u.pn < 16) {
; #pragma unroll
;                     for (int bj = 0; bj < 2; ++bj) {
;                         const int slot = 2 * u.pn + bj;
;                         bf16* dst = heads + ((size_t)slot * M + row) * HD + wc * 32 + 8 * fq;
;                         const f32x4 a = acc[ai][bj][m][0] * rs, b = acc[ai][bj][m][1] * rs;
;                         u32x4 w; w.x = pk2(a[0], a[1]); w.y = pk2(a[2], a[3]); w.z = pk2(b[0], b[1]); w.w = pk2(b[2], b[3]);
;                         *(u32x4*)dst = w;
;                     }
;                 } else if (wc == 0) {
;                     float* dst = scal + (size_t)row * 32 + 8 * fq;
;                     *(f32x4*)dst = acc[ai][0][m][0] * rs; *(f32x4*)(dst + 4) = acc[ai][0][m][1] * rs;
;                 }
.LBB0_173:
	s_nop 1
	v_add_u32_e32 v36, 0xa0, v130
	v_ashrrev_i32_e32 v37, 31, v36
	v_lshl_add_u64 v[34:35], v[36:37], 2, s[14:15]
	s_and_b64 vcc, exec, s[4:5]
	v_fmamk_f32 v34, v201, 0x3a000000, v188
	v_mul_f32_e32 v35, 0x4b800000, v34
	v_cmp_gt_f32_e64 s[6:7], s57, v34
	s_nop 1
	v_cndmask_b32_e64 v34, v34, v35, s[6:7]
	v_rsq_f32_e32 v34, v34
	s_nop 0
	v_mul_f32_e32 v35, 0x45800000, v34
	v_cndmask_b32_e64 v34, v34, v35, s[6:7]
	s_mov_b64 s[6:7], -1
	s_cbranch_vccnz .LBB0_177
	s_and_b64 vcc, exec, s[2:3]
	s_cbranch_vccnz .LBB0_176
	v_lshlrev_b64 v[38:39], 7, v[36:37]
	v_lshl_add_u64 v[46:47], v[156:157], 0, v[38:39]
	v_pk_mul_f32 v[44:45], v[32:33], v[34:35] op_sel_hi:[1,0]
	v_pk_mul_f32 v[42:43], v[30:31], v[34:35] op_sel_hi:[1,0]
	v_pk_mul_f32 v[40:41], v[28:29], v[34:35] op_sel_hi:[1,0]
	v_pk_mul_f32 v[38:39], v[26:27], v[34:35] op_sel_hi:[1,0]
	flat_store_dwordx4 v[46:47], v[42:45]
	flat_store_dwordx4 v[46:47], v[38:41] offset:16

; DI unsigned pk2(float lo, float hi) { f32x2_t v = {lo, hi}; bf16x2_t b = __builtin_convertvector(v, bf16x2_t); return __builtin_bit_cast(unsigned, b); }
;     DI void operator()(const f32x4 (&acc)[2][2][4][2], const pg8::Unit& u, int wr, int wc, int fr, int fq) const {
;     ...
;             for (int m = 0; m < 4; ++m) {
;                 const int row = u.pm * 256 + ai * 128 + wr * 64 + m * 16 + fr;
;                 const float rs = rsqrtf(ss[row] * (1.0f / DM) + EPS);
;                 if (u.pn < 16) {
; #pragma unroll
;                     for (int bj = 0; bj < 2; ++bj) {
;                         const int slot = 2 * u.pn + bj;
;                         bf16* dst = heads + ((size_t)slot * M + row) * HD + wc * 32 + 8 * fq;
;                         const f32x4 a = acc[ai][bj][m][0] * rs, b = acc[ai][bj][m][1] * rs;
;                         u32x4 w; w.x = pk2(a[0], a[1]); w.y = pk2(a[2], a[3]); w.z = pk2(b[0], b[1]); w.w = pk2(b[2], b[3]);
;                         *(u32x4*)dst = w;
;                     }
;                 } else if (wc == 0) {
;                     float* dst = scal + (size_t)row * 32 + 8 * fq;
;                     *(f32x4*)dst = acc[ai][0][m][0] * rs; *(f32x4*)(dst + 4) = acc[ai][0][m][1] * rs;
;                 }
.LBB0_179:
	s_nop 1
	v_add_u32_e32 v20, 0xb0, v130
	v_ashrrev_i32_e32 v21, 31, v20
	v_lshl_add_u64 v[18:19], v[20:21], 2, s[14:15]
	s_and_b64 vcc, exec, s[4:5]
	s_mov_b64 s[4:5], -1
	v_fmamk_f32 v18, v202, 0x3a000000, v188
	v_mul_f32_e32 v19, 0x4b800000, v18
	v_cmp_gt_f32_e64 s[6:7], s57, v18
	s_nop 1
	v_cndmask_b32_e64 v18, v18, v19, s[6:7]
	v_rsq_f32_e32 v18, v18
	s_nop 0
	v_mul_f32_e32 v19, 0x45800000, v18
	v_cndmask_b32_e64 v18, v18, v19, s[6:7]
	s_cbranch_vccnz .LBB0_183
	s_and_b64 vcc, exec, s[2:3]
	s_cbranch_vccnz .LBB0_182
	v_lshlrev_b64 v[22:23], 7, v[20:21]
	v_lshl_add_u64 v[30:31], v[156:157], 0, v[22:23]
	v_pk_mul_f32 v[28:29], v[16:17], v[18:19] op_sel_hi:[1,0]
	v_pk_mul_f32 v[26:27], v[14:15], v[18:19] op_sel_hi:[1,0]
	v_pk_mul_f32 v[24:25], v[12:13], v[18:19] op_sel_hi:[1,0]
	v_pk_mul_f32 v[22:23], v[10:11], v[18:19] op_sel_hi:[1,0]
	flat_store_dwordx4 v[30:31], v[26:29]
	flat_store_dwordx4 v[30:31], v[22:25] offset:16

; template <int MODE> DI void attn_run(AttnCtx& c, const bf16x8 (&q)[8], f32x16 (&o)[4], ldsp lds, int tid, int wv) {
;     ...
;         if (MODE == MD_FOX || ((MODE == MD_SEL || MODE == MD_CMP1 || MODE == MD_CMP2) && c.xsel)) {
;             if (i > 0) {
;                 unsigned any = 0u;
; #pragma unroll
;                 for (int k = 0; k < NWAVES; ++k) any |= xflag[((i - 1) & 1) * NWAVES + k];
;                 if (any == 0u) break;
;             }
;             if (MODE == MD_FOX) { if (i + 1 < c.ntiles) cb_next = c.cumb[(size_t)TILE_ID(i + 1) * 64 + 63]; }
;             else if (MODE == MD_SEL) { if (i + 1 < c.ntiles) cb_next = -c.slope2 * (float)(c.t - (TILE_ID(i + 1) * 64 + 63)); }
;             else { if (i + 1 < c.ntiles) cb_next = -c.slope2 * (float)(c.t - (TILE_ID(i + 1) * 1024 + 1039)); }
;         }
.LBB0_555:
	s_and_b32 s4, s94, 8
	s_xor_b32 s5, s4, 8
	s_add_i32 s6, 0, 0x22180
	s_lshl_b32 s5, s5, 2
	s_add_i32 s5, s6, s5
	v_mov_b32_e32 v0, s5
	ds_read_b128 v[116:119], v0
	ds_read_b128 v[120:123], v0 offset:16
	s_and_b64 s[10:11], s[8:9], exec
	s_andn2_b64 s[4:5], s[8:9], exec
	s_or_b64 s[18:19], s[4:5], s[10:11]
	s_waitcnt lgkmcnt(0)
	v_or3_b32 v0, v116, v117, v118
	v_or3_b32 v178, v119, v120, v121
	v_or3_b32 v0, v0, v122, v123
	v_or_b32_e32 v0, v0, v178
	v_cmp_eq_u32_e32 vcc, 0, v0
	v_cmp_ne_u32_e64 s[44:45], 0, v0
	s_cbranch_vccnz .LBB0_578
	s_cmp_lt_i32 s96, s16
	s_cselect_b64 s[4:5], -1, 0
	s_cmp_ge_i32 s96, s16
	v_mov_b32_e32 v200, 0
	s_cbranch_scc1 .LBB0_558
	s_add_u32 s10, s80, s34
	s_addc_u32 s11, s81, s35
	global_load_dword v200, v1, s[10:11]

; template <int MODE> DI void attn_run(AttnCtx& c, const bf16x8 (&q)[8], f32x16 (&o)[4], ldsp lds, int tid, int wv) {
;     ...
;         if (MODE == MD_FOX || ((MODE == MD_SEL || MODE == MD_CMP1 || MODE == MD_CMP2) && c.xsel)) {
;             if (i > 0) {
;                 unsigned any = 0u;
; #pragma unroll
;                 for (int k = 0; k < NWAVES; ++k) any |= xflag[((i - 1) & 1) * NWAVES + k];
;                 if (any == 0u) break;
;             }
;             if (MODE == MD_FOX) { if (i + 1 < c.ntiles) cb_next = c.cumb[(size_t)TILE_ID(i + 1) * 64 + 63]; }
;             else if (MODE == MD_SEL) { if (i + 1 < c.ntiles) cb_next = -c.slope2 * (float)(c.t - (TILE_ID(i + 1) * 64 + 63)); }
;             else { if (i + 1 < c.ntiles) cb_next = -c.slope2 * (float)(c.t - (TILE_ID(i + 1) * 1024 + 1039)); }
;         }
.LBB0_605:
	s_mov_b64 s[30:31], -1
	v_mov_b32_e32 v190, 0
	s_and_b64 vcc, exec, s[42:43]
	s_mov_b64 s[46:47], -1
	s_cbranch_vccnz .LBB0_608
	s_and_b32 s28, s23, 8
	s_xor_b32 s29, s28, 8
	s_add_i32 s46, 0, 0x22180
	s_lshl_b32 s29, s29, 2
	s_add_i32 s29, s46, s29
	v_mov_b32_e32 v0, s29
	ds_read_b128 v[34:37], v0
	ds_read_b128 v[38:41], v0 offset:16
	s_waitcnt lgkmcnt(0)
	v_or3_b32 v0, v34, v35, v36
	v_or3_b32 v2, v37, v38, v39
	v_or3_b32 v0, v0, v40, v41
	v_or_b32_e32 v0, v0, v2
	v_cmp_ne_u32_e32 vcc, 0, v0
	s_cbranch_vccz .LBB0_618
	v_cvt_f32_i32_e32 v0, v79
	s_cmp_lt_u32 s22, s24
	s_cselect_b64 vcc, -1, 0
	s_mov_b64 s[46:47], -1
	v_mul_f32_e64 v0, -v146, v0
	v_cndmask_b32_e32 v190, 0, v0, vcc

; template <int MODE> DI void attn_run(AttnCtx& c, const bf16x8 (&q)[8], f32x16 (&o)[4], ldsp lds, int tid, int wv) {
;     ...
;         if (MODE == MD_FOX || ((MODE == MD_SEL || MODE == MD_CMP1 || MODE == MD_CMP2) && c.xsel)) {
;             if (i > 0) {
;                 unsigned any = 0u;
; #pragma unroll
;                 for (int k = 0; k < NWAVES; ++k) any |= xflag[((i - 1) & 1) * NWAVES + k];
;                 if (any == 0u) break;
;             }
;             if (MODE == MD_FOX) { if (i + 1 < c.ntiles) cb_next = c.cumb[(size_t)TILE_ID(i + 1) * 64 + 63]; }
;             else if (MODE == MD_SEL) { if (i + 1 < c.ntiles) cb_next = -c.slope2 * (float)(c.t - (TILE_ID(i + 1) * 64 + 63)); }
;             else { if (i + 1 < c.ntiles) cb_next = -c.slope2 * (float)(c.t - (TILE_ID(i + 1) * 1024 + 1039)); }
;         }
.LBB0_652:
	s_mov_b64 s[6:7], -1
	v_mov_b32_e32 v177, 0
	s_and_b64 vcc, exec, s[42:43]
	s_mov_b64 s[8:9], -1
	s_cbranch_vccnz .LBB0_655
	s_and_b32 s8, s12, 8
	s_xor_b32 s9, s8, 8
	s_add_i32 s15, 0, 0x22180
	s_lshl_b32 s9, s9, 2
	s_add_i32 s9, s15, s9
	v_mov_b32_e32 v66, s9
	ds_read_b128 v[130:133], v66
	ds_read_b128 v[134:137], v66 offset:16
	s_waitcnt lgkmcnt(0)
	v_or3_b32 v66, v130, v131, v132
	v_or3_b32 v67, v133, v134, v135
	v_or3_b32 v66, v66, v136, v137
	v_or_b32_e32 v66, v66, v67
	v_cmp_ne_u32_e32 vcc, 0, v66
	s_cbranch_vccz .LBB0_681
	v_cvt_f32_i32_e32 v66, v175
	s_cmp_lt_u32 s14, s24
	s_cselect_b64 vcc, -1, 0
	s_mov_b64 s[8:9], -1
	v_mul_f32_e64 v66, -v146, v66
	v_cndmask_b32_e32 v177, 0, v66, vcc

; template <int MODE> DI void attn_run(AttnCtx& c, const bf16x8 (&q)[8], f32x16 (&o)[4], ldsp lds, int tid, int wv) {
;     ...
;         if (MODE == MD_FOX || ((MODE == MD_SEL || MODE == MD_CMP1 || MODE == MD_CMP2) && c.xsel)) {
;             if (i > 0) {
;                 unsigned any = 0u;
; #pragma unroll
;                 for (int k = 0; k < NWAVES; ++k) any |= xflag[((i - 1) & 1) * NWAVES + k];
;                 if (any == 0u) break;
;             }
;             if (MODE == MD_FOX) { if (i + 1 < c.ntiles) cb_next = c.cumb[(size_t)TILE_ID(i + 1) * 64 + 63]; }
;             else if (MODE == MD_SEL) { if (i + 1 < c.ntiles) cb_next = -c.slope2 * (float)(c.t - (TILE_ID(i + 1) * 64 + 63)); }
;             else { if (i + 1 < c.ntiles) cb_next = -c.slope2 * (float)(c.t - (TILE_ID(i + 1) * 1024 + 1039)); }
;         }
.LBB0_899:
	s_add_i32 s2, s34, -4
	v_mov_b32_e32 v0, s2
	ds_read_b32 v0, v0
	s_and_b64 vcc, exec, s[54:55]
	s_waitcnt lgkmcnt(0)
	v_readfirstlane_b32 s22, v0
	s_cbranch_vccz .LBB0_925
	s_and_b32 s2, s31, 8
	s_xor_b32 s3, s2, 8
	s_add_i32 s4, 0, 0x22180
	s_lshl_b32 s3, s3, 2
	s_add_i32 s3, s4, s3
	v_mov_b32_e32 v0, s3
	ds_read_b128 v[130:133], v0
	ds_read_b128 v[134:137], v0 offset:16
	s_mov_b64 s[4:5], 0
	s_mov_b64 s[2:3], 0
	s_waitcnt lgkmcnt(0)
	v_or3_b32 v0, v130, v131, v132
	v_or3_b32 v2, v133, v134, v135
	v_or3_b32 v0, v0, v136, v137
	v_or_b32_e32 v0, v0, v2
	v_cmp_ne_u32_e32 vcc, 0, v0
	s_cbranch_vccz .LBB0_904
	s_cmp_ge_i32 s21, s30
	v_mov_b32_e32 v190, 0
	s_cbranch_scc1 .LBB0_903
	v_mov_b32_e32 v0, s34
	ds_read_b32 v0, v0
	s_waitcnt lgkmcnt(0)
	v_lshlrev_b32_e32 v0, 6, v0
	v_sub_u32_e32 v0, v211, v0
	v_cvt_f32_i32_e32 v0, v0
	v_mul_f32_e64 v190, -v146, v0

; DI unsigned pk2(float lo, float hi) { f32x2_t v = {lo, hi}; bf16x2_t b = __builtin_convertvector(v, bf16x2_t); return __builtin_bit_cast(unsigned, b); }
; DI float fexp2(float x) { return __builtin_amdgcn_exp2f(x); }
;     DI void operator()(const f32x4 (&acc)[2][2][4][2], const pg8::Unit& u, int wr, int wc, int fr, int fq) const {
;     ...
;         for (int ai = 0; ai < 2; ++ai)
; #pragma unroll
;             for (int m = 0; m < 4; ++m) {
;                 const int row = u.pm * 256 + ai * 128 + wr * 64 + m * 16 + fr;
;                 const float rs = rsqrtf(ss[row] * (1.0f / DM) + EPS);
;                 float o[8];
; #pragma unroll
;                 for (int n = 0; n < 2; ++n)
; #pragma unroll
;                     for (int e = 0; e < 4; ++e) { const float g = acc[ai][0][m][n][e] * rs, up = acc[ai][1][m][n][e] * rs;
;                         o[4 * n + e] = g * up * __builtin_amdgcn_rcpf(1.0f + fexp2(-LOG2E * g)); }
;                 u32x4 w; w.x = pk2(o[0], o[1]); w.y = pk2(o[2], o[3]); w.z = pk2(o[4], o[5]); w.w = pk2(o[6], o[7]);
;                 *(u32x4*)(h + (size_t)row * FF + u.pn * 128 + wc * 32 + 8 * fq) = w;
.LBB0_1243:
	v_lshl_add_u32 v142, s18, 8, v146
	v_ashrrev_i32_e32 v143, 31, v142
	v_lshl_add_u64 v[144:145], v[142:143], 2, s[2:3]
	flat_load_dword v143, v[144:145]
	flat_load_dword v160, v[144:145] offset:64
	flat_load_dword v161, v[144:145] offset:128
	flat_load_dword v162, v[144:145] offset:192
	flat_load_dword v163, v[144:145] offset:512
	flat_load_dword v164, v[144:145] offset:576
	flat_load_dword v165, v[144:145] offset:640
	flat_load_dword v166, v[144:145] offset:704
	v_readlane_b32 s20, v254, 56
	s_lshl_b32 s18, s19, 7
	v_readlane_b32 s21, v254, 57
	s_ashr_i32 s19, s18, 31
	s_movk_i32 s9, 0x2c00
	s_lshl_b64 s[18:19], s[18:19], 1
	s_waitcnt vmcnt(0) lgkmcnt(0)
	v_fmamk_f32 v143, v143, 0x3a000000, v188
	v_cmp_gt_f32_e32 vcc, s52, v143
	v_mul_f32_e32 v149, 0x4b800000, v143
	s_nop 0
	v_cndmask_b32_e32 v143, v143, v149, vcc
	v_rsq_f32_e32 v143, v143
	s_nop 0
	v_mul_f32_e32 v149, 0x45800000, v143
	v_cndmask_b32_e32 v150, v143, v149, vcc
	v_pk_mul_f32 v[126:127], v[126:127], v[150:151] op_sel_hi:[1,0]
	v_pk_mul_f32 v[118:119], v[118:119], v[150:151] op_sel_hi:[1,0]
	v_mul_f32_e32 v143, 0xbfb8aa3b, v126
	v_pk_mul_f32 v[118:119], v[126:127], v[118:119]
	v_mul_f32_e32 v126, 0xbfb8aa3b, v127
	v_exp_f32_e32 v126, v126
	v_pk_mul_f32 v[120:121], v[120:121], v[150:151] op_sel_hi:[1,0]
	v_pk_mul_f32 v[122:123], v[122:123], v[150:151] op_sel_hi:[1,0]
	v_pk_mul_f32 v[114:115], v[114:115], v[150:151] op_sel_hi:[1,0]
	v_add_f32_e32 v126, 1.0, v126
	v_rcp_f32_e32 v153, v126
	v_pk_mul_f32 v[126:127], v[128:129], v[150:151] op_sel_hi:[1,0]
	v_pk_mul_f32 v[114:115], v[122:123], v[114:115]
	v_mul_f32_e32 v128, 0xbfb8aa3b, v126
	v_pk_mul_f32 v[120:121], v[126:127], v[120:121]
	v_mul_f32_e32 v126, 0xbfb8aa3b, v127
	v_exp_f32_e32 v126, v126
	v_exp_f32_e32 v143, v143
	v_exp_f32_e32 v128, v128
	v_pk_mul_f32 v[116:117], v[116:117], v[150:151] op_sel_hi:[1,0]
	v_add_f32_e32 v126, 1.0, v126
	v_rcp_f32_e32 v129, v126
	v_mul_f32_e32 v126, 0xbfb8aa3b, v122
	v_mul_f32_e32 v122, 0xbfb8aa3b, v123
	v_exp_f32_e32 v126, v126
	v_exp_f32_e32 v122, v122
	v_add_f32_e32 v143, 1.0, v143
	v_rcp_f32_e32 v152, v143
	v_add_f32_e32 v126, 1.0, v126
	v_add_f32_e32 v122, 1.0, v122
	v_rcp_f32_e32 v126, v126
	v_rcp_f32_e32 v127, v122
	v_add_f32_e32 v128, 1.0, v128
	v_rcp_f32_e32 v128, v128
	v_pk_mul_f32 v[118:119], v[118:119], v[152:153]
	v_pk_mul_f32 v[122:123], v[114:115], v[126:127]
	v_pk_mul_f32 v[114:115], v[124:125], v[150:151] op_sel_hi:[1,0]
	v_pk_mul_f32 v[120:121], v[120:121], v[128:129]
	v_mul_f32_e32 v124, 0xbfb8aa3b, v114
	v_pk_mul_f32 v[116:117], v[114:115], v[116:117]
	v_mul_f32_e32 v114, 0xbfb8aa3b, v115
	v_exp_f32_e32 v124, v124
	v_exp_f32_e32 v114, v114
	v_cvt_pk_bf16_f32 v115, v120, v121
	v_add_f32_e32 v124, 1.0, v124
	v_add_f32_e32 v114, 1.0, v114
	v_rcp_f32_e32 v124, v124
	v_rcp_f32_e32 v125, v114
	v_cvt_pk_bf16_f32 v114, v118, v119
	v_mov_b64_e32 v[118:119], s[20:21]
	v_mad_i64_i32 v[120:121], s[20:21], v142, s9, v[118:119]
	v_lshl_add_u64 v[120:121], v[120:121], 0, s[18:19]
	v_pk_mul_f32 v[124:125], v[116:117], v[124:125]
	v_lshl_add_u64 v[120:121], v[120:121], 0, s[16:17]
	v_cvt_pk_bf16_f32 v116, v122, v123
	v_cvt_pk_bf16_f32 v117, v124, v125
	v_lshl_add_u64 v[120:121], v[120:121], 0, v[0:1]
	flat_store_dwordx4 v[120:121], v[114:117]
	s_nop 0
	s_nop 0
	v_or_b32_e32 v115, 16, v142
	v_fmamk_f32 v114, v160, 0x3a000000, v188
	v_cmp_gt_f32_e32 vcc, s52, v114
	v_mul_f32_e32 v116, 0x4b800000, v114
	s_nop 0
	v_cndmask_b32_e32 v114, v114, v116, vcc
	v_rsq_f32_e32 v114, v114
	s_nop 0
	v_mul_f32_e32 v116, 0x45800000, v114
	v_cndmask_b32_e32 v114, v114, v116, vcc
	v_pk_mul_f32 v[110:111], v[110:111], v[114:115] op_sel_hi:[1,0]
	v_pk_mul_f32 v[102:103], v[102:103], v[114:115] op_sel_hi:[1,0]
	v_mul_f32_e32 v116, 0xbfb8aa3b, v110
	v_pk_mul_f32 v[102:103], v[110:111], v[102:103]
	v_mul_f32_e32 v110, 0xbfb8aa3b, v111
	v_exp_f32_e32 v110, v110
	v_pk_mul_f32 v[104:105], v[104:105], v[114:115] op_sel_hi:[1,0]
	v_pk_mul_f32 v[106:107], v[106:107], v[114:115] op_sel_hi:[1,0]
	v_pk_mul_f32 v[98:99], v[98:99], v[114:115] op_sel_hi:[1,0]
	v_add_f32_e32 v110, 1.0, v110
	v_rcp_f32_e32 v117, v110
	v_pk_mul_f32 v[110:111], v[112:113], v[114:115] op_sel_hi:[1,0]
	v_pk_mul_f32 v[98:99], v[106:107], v[98:99]
	v_mul_f32_e32 v112, 0xbfb8aa3b, v110
	v_pk_mul_f32 v[104:105], v[110:111], v[104:105]
	v_mul_f32_e32 v110, 0xbfb8aa3b, v111
	v_exp_f32_e32 v110, v110
	v_exp_f32_e32 v116, v116
	v_pk_mul_f32 v[100:101], v[100:101], v[114:115] op_sel_hi:[1,0]
	v_exp_f32_e32 v112, v112
	v_add_f32_e32 v110, 1.0, v110
	v_rcp_f32_e32 v113, v110
	v_mul_f32_e32 v110, 0xbfb8aa3b, v106
	v_mul_f32_e32 v106, 0xbfb8aa3b, v107
	v_exp_f32_e32 v110, v110
	v_exp_f32_e32 v106, v106
	v_add_f32_e32 v116, 1.0, v116
	v_rcp_f32_e32 v116, v116
	v_add_f32_e32 v110, 1.0, v110
	v_add_f32_e32 v106, 1.0, v106
	v_rcp_f32_e32 v110, v110
	v_rcp_f32_e32 v111, v106
	v_add_f32_e32 v112, 1.0, v112
	v_rcp_f32_e32 v112, v112
	v_pk_mul_f32 v[102:103], v[102:103], v[116:117]
	v_pk_mul_f32 v[106:107], v[98:99], v[110:111]
	v_pk_mul_f32 v[98:99], v[108:109], v[114:115] op_sel_hi:[1,0]
	v_pk_mul_f32 v[104:105], v[104:105], v[112:113]
	v_mul_f32_e32 v108, 0xbfb8aa3b, v98
	v_pk_mul_f32 v[100:101], v[98:99], v[100:101]
	v_mul_f32_e32 v98, 0xbfb8aa3b, v99
	v_exp_f32_e32 v108, v108
	v_exp_f32_e32 v98, v98
	v_cvt_pk_bf16_f32 v99, v104, v105
	v_add_f32_e32 v108, 1.0, v108
	v_add_f32_e32 v98, 1.0, v98
	v_rcp_f32_e32 v108, v108
	v_rcp_f32_e32 v109, v98
	v_cvt_pk_bf16_f32 v98, v102, v103
	v_mad_i64_i32 v[102:103], s[20:21], v115, s9, v[118:119]
	v_lshl_add_u64 v[102:103], v[102:103], 0, s[18:19]
	v_pk_mul_f32 v[108:109], v[100:101], v[108:109]
; DI unsigned pk2(float lo, float hi) { f32x2_t v = {lo, hi}; bf16x2_t b = __builtin_convertvector(v, bf16x2_t); return __builtin_bit_cast(unsigned, b); }
; DI float fexp2(float x) { return __builtin_amdgcn_exp2f(x); }
;     DI void operator()(const f32x4 (&acc)[2][2][4][2], const pg8::Unit& u, int wr, int wc, int fr, int fq) const {
;     ...
;         for (int ai = 0; ai < 2; ++ai)
; #pragma unroll
;             for (int m = 0; m < 4; ++m) {
;                 const int row = u.pm * 256 + ai * 128 + wr * 64 + m * 16 + fr;
;                 const float rs = rsqrtf(ss[row] * (1.0f / DM) + EPS);
;                 float o[8];
; #pragma unroll
;                 for (int n = 0; n < 2; ++n)
; #pragma unroll
;                     for (int e = 0; e < 4; ++e) { const float g = acc[ai][0][m][n][e] * rs, up = acc[ai][1][m][n][e] * rs;
;                         o[4 * n + e] = g * up * __builtin_amdgcn_rcpf(1.0f + fexp2(-LOG2E * g)); }
;                 u32x4 w; w.x = pk2(o[0], o[1]); w.y = pk2(o[2], o[3]); w.z = pk2(o[4], o[5]); w.w = pk2(o[6], o[7]);
;                 *(u32x4*)(h + (size_t)row * FF + u.pn * 128 + wc * 32 + 8 * fq) = w;
	v_lshl_add_u64 v[102:103], v[102:103], 0, s[16:17]
	v_cvt_pk_bf16_f32 v100, v106, v107
	v_cvt_pk_bf16_f32 v101, v108, v109
	v_lshl_add_u64 v[102:103], v[102:103], 0, v[0:1]
	flat_store_dwordx4 v[102:103], v[98:101]
	s_nop 0
	s_nop 0
	v_or_b32_e32 v99, 32, v142
	v_fmamk_f32 v98, v161, 0x3a000000, v188
	v_cmp_gt_f32_e32 vcc, s52, v98
	v_mul_f32_e32 v100, 0x4b800000, v98
	s_nop 0
	v_cndmask_b32_e32 v98, v98, v100, vcc
	v_rsq_f32_e32 v98, v98
	s_nop 0
	v_mul_f32_e32 v100, 0x45800000, v98
	v_cndmask_b32_e32 v98, v98, v100, vcc
	v_pk_mul_f32 v[94:95], v[94:95], v[98:99] op_sel_hi:[1,0]
	v_pk_mul_f32 v[86:87], v[86:87], v[98:99] op_sel_hi:[1,0]
	v_mul_f32_e32 v100, 0xbfb8aa3b, v94
	v_pk_mul_f32 v[86:87], v[94:95], v[86:87]
	v_mul_f32_e32 v94, 0xbfb8aa3b, v95
	v_exp_f32_e32 v94, v94
	v_pk_mul_f32 v[88:89], v[88:89], v[98:99] op_sel_hi:[1,0]
	v_pk_mul_f32 v[90:91], v[90:91], v[98:99] op_sel_hi:[1,0]
	v_pk_mul_f32 v[82:83], v[82:83], v[98:99] op_sel_hi:[1,0]
	v_add_f32_e32 v94, 1.0, v94
	v_rcp_f32_e32 v101, v94
	v_pk_mul_f32 v[94:95], v[96:97], v[98:99] op_sel_hi:[1,0]
	v_pk_mul_f32 v[82:83], v[90:91], v[82:83]
	v_mul_f32_e32 v96, 0xbfb8aa3b, v94
	v_pk_mul_f32 v[88:89], v[94:95], v[88:89]
	v_mul_f32_e32 v94, 0xbfb8aa3b, v95
	v_exp_f32_e32 v94, v94
	v_exp_f32_e32 v100, v100
	v_pk_mul_f32 v[84:85], v[84:85], v[98:99] op_sel_hi:[1,0]
	v_exp_f32_e32 v96, v96
	v_add_f32_e32 v94, 1.0, v94
	v_rcp_f32_e32 v97, v94
	v_mul_f32_e32 v94, 0xbfb8aa3b, v90
	v_mul_f32_e32 v90, 0xbfb8aa3b, v91
	v_exp_f32_e32 v94, v94
	v_exp_f32_e32 v90, v90
	v_add_f32_e32 v100, 1.0, v100
	v_rcp_f32_e32 v100, v100
	v_add_f32_e32 v94, 1.0, v94
	v_add_f32_e32 v90, 1.0, v90
	v_rcp_f32_e32 v94, v94
	v_rcp_f32_e32 v95, v90
	v_add_f32_e32 v96, 1.0, v96
	v_rcp_f32_e32 v96, v96
	v_pk_mul_f32 v[86:87], v[86:87], v[100:101]
	v_pk_mul_f32 v[90:91], v[82:83], v[94:95]
	v_pk_mul_f32 v[82:83], v[92:93], v[98:99] op_sel_hi:[1,0]
	v_pk_mul_f32 v[88:89], v[88:89], v[96:97]
	v_mul_f32_e32 v92, 0xbfb8aa3b, v82
	v_pk_mul_f32 v[84:85], v[82:83], v[84:85]
	v_mul_f32_e32 v82, 0xbfb8aa3b, v83
	v_exp_f32_e32 v92, v92
	v_exp_f32_e32 v82, v82
	v_cvt_pk_bf16_f32 v83, v88, v89
	v_add_f32_e32 v92, 1.0, v92
	v_add_f32_e32 v82, 1.0, v82
	v_rcp_f32_e32 v92, v92
	v_rcp_f32_e32 v93, v82
	v_cvt_pk_bf16_f32 v82, v86, v87
	v_mad_i64_i32 v[86:87], s[20:21], v99, s9, v[118:119]
	v_lshl_add_u64 v[86:87], v[86:87], 0, s[18:19]
	v_pk_mul_f32 v[92:93], v[84:85], v[92:93]
	v_lshl_add_u64 v[86:87], v[86:87], 0, s[16:17]
	v_cvt_pk_bf16_f32 v84, v90, v91
	v_cvt_pk_bf16_f32 v85, v92, v93
	v_lshl_add_u64 v[86:87], v[86:87], 0, v[0:1]
	flat_store_dwordx4 v[86:87], v[82:85]
	s_nop 0
	s_nop 0
	v_or_b32_e32 v83, 48, v142
	v_fmamk_f32 v82, v162, 0x3a000000, v188
	v_cmp_gt_f32_e32 vcc, s52, v82
	v_mul_f32_e32 v84, 0x4b800000, v82
	s_nop 0
	v_cndmask_b32_e32 v82, v82, v84, vcc
	v_rsq_f32_e32 v82, v82
	s_nop 0
	v_mul_f32_e32 v84, 0x45800000, v82
	v_cndmask_b32_e32 v82, v82, v84, vcc
	v_pk_mul_f32 v[78:79], v[78:79], v[82:83] op_sel_hi:[1,0]
	v_pk_mul_f32 v[70:71], v[70:71], v[82:83] op_sel_hi:[1,0]
	v_mul_f32_e32 v84, 0xbfb8aa3b, v78
	v_pk_mul_f32 v[70:71], v[78:79], v[70:71]
	v_mul_f32_e32 v78, 0xbfb8aa3b, v79
	v_exp_f32_e32 v78, v78
	v_pk_mul_f32 v[72:73], v[72:73], v[82:83] op_sel_hi:[1,0]
	v_pk_mul_f32 v[74:75], v[74:75], v[82:83] op_sel_hi:[1,0]
	v_pk_mul_f32 v[66:67], v[66:67], v[82:83] op_sel_hi:[1,0]
	v_add_f32_e32 v78, 1.0, v78
	v_rcp_f32_e32 v85, v78
	v_pk_mul_f32 v[78:79], v[80:81], v[82:83] op_sel_hi:[1,0]
	v_pk_mul_f32 v[66:67], v[74:75], v[66:67]
	v_mul_f32_e32 v80, 0xbfb8aa3b, v78
	v_pk_mul_f32 v[72:73], v[78:79], v[72:73]
	v_mul_f32_e32 v78, 0xbfb8aa3b, v79
	v_exp_f32_e32 v78, v78
	v_exp_f32_e32 v84, v84
	v_pk_mul_f32 v[68:69], v[68:69], v[82:83] op_sel_hi:[1,0]
	v_exp_f32_e32 v80, v80
	v_add_f32_e32 v78, 1.0, v78
	v_rcp_f32_e32 v81, v78
	v_mul_f32_e32 v78, 0xbfb8aa3b, v74
	v_mul_f32_e32 v74, 0xbfb8aa3b, v75
	v_exp_f32_e32 v78, v78
	v_exp_f32_e32 v74, v74
	v_add_f32_e32 v84, 1.0, v84
	v_rcp_f32_e32 v84, v84
	v_add_f32_e32 v78, 1.0, v78
	v_add_f32_e32 v74, 1.0, v74
	v_rcp_f32_e32 v78, v78
	v_rcp_f32_e32 v79, v74
	v_add_f32_e32 v80, 1.0, v80
	v_rcp_f32_e32 v80, v80
	v_pk_mul_f32 v[70:71], v[70:71], v[84:85]
	v_pk_mul_f32 v[74:75], v[66:67], v[78:79]
	v_pk_mul_f32 v[66:67], v[76:77], v[82:83] op_sel_hi:[1,0]
	v_pk_mul_f32 v[72:73], v[72:73], v[80:81]
	v_mul_f32_e32 v76, 0xbfb8aa3b, v66
	v_pk_mul_f32 v[68:69], v[66:67], v[68:69]
	v_mul_f32_e32 v66, 0xbfb8aa3b, v67
	v_exp_f32_e32 v76, v76
	v_exp_f32_e32 v66, v66
	v_cvt_pk_bf16_f32 v67, v72, v73
	v_add_f32_e32 v76, 1.0, v76
	v_add_f32_e32 v66, 1.0, v66
	v_rcp_f32_e32 v76, v76
	v_rcp_f32_e32 v77, v66
	v_cvt_pk_bf16_f32 v66, v70, v71
	v_mad_i64_i32 v[70:71], s[20:21], v83, s9, v[118:119]
	v_lshl_add_u64 v[70:71], v[70:71], 0, s[18:19]
	v_pk_mul_f32 v[76:77], v[68:69], v[76:77]
	v_lshl_add_u64 v[70:71], v[70:71], 0, s[16:17]
	v_cvt_pk_bf16_f32 v68, v74, v75
	v_cvt_pk_bf16_f32 v69, v76, v77
	v_lshl_add_u64 v[70:71], v[70:71], 0, v[0:1]
	flat_store_dwordx4 v[70:71], v[66:69]
	s_nop 0
	s_nop 0
	v_add_u32_e32 v67, 0x80, v142
	v_fmamk_f32 v66, v163, 0x3a000000, v188
	v_cmp_gt_f32_e32 vcc, s52, v66
	v_mul_f32_e32 v68, 0x4b800000, v66
	s_nop 0
	v_cndmask_b32_e32 v66, v66, v68, vcc
	v_rsq_f32_e32 v66, v66
	s_nop 0
	v_mul_f32_e32 v68, 0x45800000, v66
	v_cndmask_b32_e32 v66, v66, v68, vcc
	v_pk_mul_f32 v[62:63], v[62:63], v[66:67] op_sel_hi:[1,0]
	v_pk_mul_f32 v[54:55], v[54:55], v[66:67] op_sel_hi:[1,0]
	v_mul_f32_e32 v68, 0xbfb8aa3b, v62
	v_pk_mul_f32 v[54:55], v[62:63], v[54:55]
	v_mul_f32_e32 v62, 0xbfb8aa3b, v63
	v_exp_f32_e32 v62, v62
	v_pk_mul_f32 v[56:57], v[56:57], v[66:67] op_sel_hi:[1,0]
; DI unsigned pk2(float lo, float hi) { f32x2_t v = {lo, hi}; bf16x2_t b = __builtin_convertvector(v, bf16x2_t); return __builtin_bit_cast(unsigned, b); }
; DI float fexp2(float x) { return __builtin_amdgcn_exp2f(x); }
;     DI void operator()(const f32x4 (&acc)[2][2][4][2], const pg8::Unit& u, int wr, int wc, int fr, int fq) const {
;     ...
;         for (int ai = 0; ai < 2; ++ai)
; #pragma unroll
;             for (int m = 0; m < 4; ++m) {
;                 const int row = u.pm * 256 + ai * 128 + wr * 64 + m * 16 + fr;
;                 const float rs = rsqrtf(ss[row] * (1.0f / DM) + EPS);
;                 float o[8];
; #pragma unroll
;                 for (int n = 0; n < 2; ++n)
; #pragma unroll
;                     for (int e = 0; e < 4; ++e) { const float g = acc[ai][0][m][n][e] * rs, up = acc[ai][1][m][n][e] * rs;
;                         o[4 * n + e] = g * up * __builtin_amdgcn_rcpf(1.0f + fexp2(-LOG2E * g)); }
;                 u32x4 w; w.x = pk2(o[0], o[1]); w.y = pk2(o[2], o[3]); w.z = pk2(o[4], o[5]); w.w = pk2(o[6], o[7]);
;                 *(u32x4*)(h + (size_t)row * FF + u.pn * 128 + wc * 32 + 8 * fq) = w;
	v_pk_mul_f32 v[58:59], v[58:59], v[66:67] op_sel_hi:[1,0]
	v_pk_mul_f32 v[50:51], v[50:51], v[66:67] op_sel_hi:[1,0]
	v_add_f32_e32 v62, 1.0, v62
	v_rcp_f32_e32 v69, v62
	v_pk_mul_f32 v[62:63], v[64:65], v[66:67] op_sel_hi:[1,0]
	v_pk_mul_f32 v[50:51], v[58:59], v[50:51]
	v_mul_f32_e32 v64, 0xbfb8aa3b, v62
	v_pk_mul_f32 v[56:57], v[62:63], v[56:57]
	v_mul_f32_e32 v62, 0xbfb8aa3b, v63
	v_exp_f32_e32 v62, v62
	v_exp_f32_e32 v68, v68
	v_pk_mul_f32 v[52:53], v[52:53], v[66:67] op_sel_hi:[1,0]
	v_exp_f32_e32 v64, v64
	v_add_f32_e32 v62, 1.0, v62
	v_rcp_f32_e32 v65, v62
	v_mul_f32_e32 v62, 0xbfb8aa3b, v58
	v_mul_f32_e32 v58, 0xbfb8aa3b, v59
	v_exp_f32_e32 v62, v62
	v_exp_f32_e32 v58, v58
	v_add_f32_e32 v68, 1.0, v68
	v_rcp_f32_e32 v68, v68
	v_add_f32_e32 v62, 1.0, v62
	v_add_f32_e32 v58, 1.0, v58
	v_rcp_f32_e32 v62, v62
	v_rcp_f32_e32 v63, v58
	v_add_f32_e32 v64, 1.0, v64
	v_rcp_f32_e32 v64, v64
	v_pk_mul_f32 v[54:55], v[54:55], v[68:69]
	v_pk_mul_f32 v[58:59], v[50:51], v[62:63]
	v_pk_mul_f32 v[50:51], v[60:61], v[66:67] op_sel_hi:[1,0]
	v_pk_mul_f32 v[56:57], v[56:57], v[64:65]
	v_mul_f32_e32 v60, 0xbfb8aa3b, v50
	v_pk_mul_f32 v[52:53], v[50:51], v[52:53]
	v_mul_f32_e32 v50, 0xbfb8aa3b, v51
	v_exp_f32_e32 v60, v60
	v_exp_f32_e32 v50, v50
	v_cvt_pk_bf16_f32 v51, v56, v57
	v_add_f32_e32 v60, 1.0, v60
	v_add_f32_e32 v50, 1.0, v50
	v_rcp_f32_e32 v60, v60
	v_rcp_f32_e32 v61, v50
	v_cvt_pk_bf16_f32 v50, v54, v55
	v_mad_i64_i32 v[54:55], s[20:21], v67, s9, v[118:119]
	v_lshl_add_u64 v[54:55], v[54:55], 0, s[18:19]
	v_pk_mul_f32 v[60:61], v[52:53], v[60:61]
	v_lshl_add_u64 v[54:55], v[54:55], 0, s[16:17]
	v_cvt_pk_bf16_f32 v52, v58, v59
	v_cvt_pk_bf16_f32 v53, v60, v61
	v_lshl_add_u64 v[54:55], v[54:55], 0, v[0:1]
	flat_store_dwordx4 v[54:55], v[50:53]
	s_nop 0
	s_nop 0
	v_add_u32_e32 v51, 0x90, v142
	v_fmamk_f32 v50, v164, 0x3a000000, v188
	v_cmp_gt_f32_e32 vcc, s52, v50
	v_mul_f32_e32 v52, 0x4b800000, v50
	s_nop 0
	v_cndmask_b32_e32 v50, v50, v52, vcc
	v_rsq_f32_e32 v50, v50
	s_nop 0
	v_mul_f32_e32 v52, 0x45800000, v50
	v_cndmask_b32_e32 v50, v50, v52, vcc
	v_pk_mul_f32 v[46:47], v[46:47], v[50:51] op_sel_hi:[1,0]
	v_pk_mul_f32 v[38:39], v[38:39], v[50:51] op_sel_hi:[1,0]
	v_mul_f32_e32 v52, 0xbfb8aa3b, v46
	v_pk_mul_f32 v[38:39], v[46:47], v[38:39]
	v_mul_f32_e32 v46, 0xbfb8aa3b, v47
	v_exp_f32_e32 v46, v46
	v_pk_mul_f32 v[40:41], v[40:41], v[50:51] op_sel_hi:[1,0]
	v_pk_mul_f32 v[42:43], v[42:43], v[50:51] op_sel_hi:[1,0]
	v_pk_mul_f32 v[34:35], v[34:35], v[50:51] op_sel_hi:[1,0]
	v_add_f32_e32 v46, 1.0, v46
	v_rcp_f32_e32 v53, v46
	v_pk_mul_f32 v[46:47], v[48:49], v[50:51] op_sel_hi:[1,0]
	v_pk_mul_f32 v[34:35], v[42:43], v[34:35]
	v_mul_f32_e32 v48, 0xbfb8aa3b, v46
	v_pk_mul_f32 v[40:41], v[46:47], v[40:41]
	v_mul_f32_e32 v46, 0xbfb8aa3b, v47
	v_exp_f32_e32 v46, v46
	v_exp_f32_e32 v52, v52
	v_pk_mul_f32 v[36:37], v[36:37], v[50:51] op_sel_hi:[1,0]
	v_exp_f32_e32 v48, v48
	v_add_f32_e32 v46, 1.0, v46
	v_rcp_f32_e32 v49, v46
	v_mul_f32_e32 v46, 0xbfb8aa3b, v42
	v_mul_f32_e32 v42, 0xbfb8aa3b, v43
	v_exp_f32_e32 v46, v46
	v_exp_f32_e32 v42, v42
	v_add_f32_e32 v52, 1.0, v52
	v_rcp_f32_e32 v52, v52
	v_add_f32_e32 v46, 1.0, v46
	v_add_f32_e32 v42, 1.0, v42
	v_rcp_f32_e32 v46, v46
	v_rcp_f32_e32 v47, v42
	v_add_f32_e32 v48, 1.0, v48
	v_rcp_f32_e32 v48, v48
	v_pk_mul_f32 v[38:39], v[38:39], v[52:53]
	v_pk_mul_f32 v[42:43], v[34:35], v[46:47]
	v_pk_mul_f32 v[34:35], v[44:45], v[50:51] op_sel_hi:[1,0]
	v_pk_mul_f32 v[40:41], v[40:41], v[48:49]
	v_mul_f32_e32 v44, 0xbfb8aa3b, v34
	v_pk_mul_f32 v[36:37], v[34:35], v[36:37]
	v_mul_f32_e32 v34, 0xbfb8aa3b, v35
	v_exp_f32_e32 v44, v44
	v_exp_f32_e32 v34, v34
	v_cvt_pk_bf16_f32 v35, v40, v41
	v_add_f32_e32 v44, 1.0, v44
	v_add_f32_e32 v34, 1.0, v34
	v_rcp_f32_e32 v44, v44
	v_rcp_f32_e32 v45, v34
	v_cvt_pk_bf16_f32 v34, v38, v39
	v_mad_i64_i32 v[38:39], s[20:21], v51, s9, v[118:119]
	v_lshl_add_u64 v[38:39], v[38:39], 0, s[18:19]
	v_pk_mul_f32 v[44:45], v[36:37], v[44:45]
	v_lshl_add_u64 v[38:39], v[38:39], 0, s[16:17]
	v_cvt_pk_bf16_f32 v36, v42, v43
	v_cvt_pk_bf16_f32 v37, v44, v45
	v_lshl_add_u64 v[38:39], v[38:39], 0, v[0:1]
	flat_store_dwordx4 v[38:39], v[34:37]
	s_nop 0
	s_nop 0
	v_add_u32_e32 v35, 0xa0, v142
	v_fmamk_f32 v34, v165, 0x3a000000, v188
	v_cmp_gt_f32_e32 vcc, s52, v34
	v_mul_f32_e32 v36, 0x4b800000, v34
	s_nop 0
	v_cndmask_b32_e32 v34, v34, v36, vcc
	v_rsq_f32_e32 v34, v34
	s_nop 0
	v_mul_f32_e32 v36, 0x45800000, v34
	v_cndmask_b32_e32 v34, v34, v36, vcc
	v_pk_mul_f32 v[30:31], v[30:31], v[34:35] op_sel_hi:[1,0]
; #define PG8_BAR __builtin_amdgcn_s_barrier()
; DI unsigned pk2(float lo, float hi) { f32x2_t v = {lo, hi}; bf16x2_t b = __builtin_convertvector(v, bf16x2_t); return __builtin_bit_cast(unsigned, b); }
; DI float fexp2(float x) { return __builtin_amdgcn_exp2f(x); }
; template <class Epi, class Sched, bool ALIGN_EPI = false, bool SP2 = false>
; __device__ __forceinline__ void gemm_phase(PG8_LAS unsigned char* lds, const Gemm g, const Sched& S, const Epi& E, int wv) {
;     ...
;         if constexpr (!Epi::AFTER_DRAIN) { E(acc, cur, wr, wc, fr, fq); S.done(cur); }
;         if (!has_next) break;
; #pragma unroll
;         for (int a = 0; a < 2; ++a)
; #pragma unroll
;             for (int b = 0; b < 2; ++b)
; #pragma unroll
;                 for (int m = 0; m < 4; ++m)
; #pragma unroll
;                     for (int n = 0; n < 2; ++n) acc[a][b][m][n] = (f32x4){0.f, 0.f, 0.f, 0.f};
;         cur = nxt; cA = nA; cB = nB; ++ui;
;         if constexpr (ALIGN_EPI) { if (wr == 1) PG8_BAR; }
;     DI void operator()(const f32x4 (&acc)[2][2][4][2], const pg8::Unit& u, int wr, int wc, int fr, int fq) const {
;     ...
;         for (int ai = 0; ai < 2; ++ai)
; #pragma unroll
;             for (int m = 0; m < 4; ++m) {
;                 const int row = u.pm * 256 + ai * 128 + wr * 64 + m * 16 + fr;
;                 const float rs = rsqrtf(ss[row] * (1.0f / DM) + EPS);
;                 float o[8];
; #pragma unroll
;                 for (int n = 0; n < 2; ++n)
; #pragma unroll
;                     for (int e = 0; e < 4; ++e) { const float g = acc[ai][0][m][n][e] * rs, up = acc[ai][1][m][n][e] * rs;
;                         o[4 * n + e] = g * up * __builtin_amdgcn_rcpf(1.0f + fexp2(-LOG2E * g)); }
;                 u32x4 w; w.x = pk2(o[0], o[1]); w.y = pk2(o[2], o[3]); w.z = pk2(o[4], o[5]); w.w = pk2(o[6], o[7]);
;                 *(u32x4*)(h + (size_t)row * FF + u.pn * 128 + wc * 32 + 8 * fq) = w;
	v_pk_mul_f32 v[22:23], v[22:23], v[34:35] op_sel_hi:[1,0]
	v_mul_f32_e32 v36, 0xbfb8aa3b, v30
	v_pk_mul_f32 v[22:23], v[30:31], v[22:23]
	v_mul_f32_e32 v30, 0xbfb8aa3b, v31
	v_exp_f32_e32 v30, v30
	v_pk_mul_f32 v[24:25], v[24:25], v[34:35] op_sel_hi:[1,0]
	v_pk_mul_f32 v[26:27], v[26:27], v[34:35] op_sel_hi:[1,0]
	v_pk_mul_f32 v[18:19], v[18:19], v[34:35] op_sel_hi:[1,0]
	v_add_f32_e32 v30, 1.0, v30
	v_rcp_f32_e32 v37, v30
	v_pk_mul_f32 v[30:31], v[32:33], v[34:35] op_sel_hi:[1,0]
	v_pk_mul_f32 v[18:19], v[26:27], v[18:19]
	v_mul_f32_e32 v32, 0xbfb8aa3b, v30
	v_pk_mul_f32 v[24:25], v[30:31], v[24:25]
	v_mul_f32_e32 v30, 0xbfb8aa3b, v31
	v_exp_f32_e32 v30, v30
	v_exp_f32_e32 v36, v36
	v_pk_mul_f32 v[20:21], v[20:21], v[34:35] op_sel_hi:[1,0]
	v_exp_f32_e32 v32, v32
	v_add_f32_e32 v30, 1.0, v30
	v_rcp_f32_e32 v33, v30
	v_mul_f32_e32 v30, 0xbfb8aa3b, v26
	v_mul_f32_e32 v26, 0xbfb8aa3b, v27
	v_exp_f32_e32 v30, v30
	v_exp_f32_e32 v26, v26
	v_add_f32_e32 v36, 1.0, v36
	v_rcp_f32_e32 v36, v36
	v_add_f32_e32 v30, 1.0, v30
	v_add_f32_e32 v26, 1.0, v26
	v_rcp_f32_e32 v30, v30
	v_rcp_f32_e32 v31, v26
	v_add_f32_e32 v32, 1.0, v32
	v_rcp_f32_e32 v32, v32
	v_pk_mul_f32 v[22:23], v[22:23], v[36:37]
	v_pk_mul_f32 v[26:27], v[18:19], v[30:31]
	v_pk_mul_f32 v[18:19], v[28:29], v[34:35] op_sel_hi:[1,0]
	v_pk_mul_f32 v[24:25], v[24:25], v[32:33]
	v_mul_f32_e32 v28, 0xbfb8aa3b, v18
	v_pk_mul_f32 v[20:21], v[18:19], v[20:21]
	v_mul_f32_e32 v18, 0xbfb8aa3b, v19
	v_exp_f32_e32 v28, v28
	v_exp_f32_e32 v18, v18
	v_cvt_pk_bf16_f32 v19, v24, v25
	v_add_f32_e32 v28, 1.0, v28
	v_add_f32_e32 v18, 1.0, v18
	v_rcp_f32_e32 v28, v28
	v_rcp_f32_e32 v29, v18
	v_cvt_pk_bf16_f32 v18, v22, v23
	v_mad_i64_i32 v[22:23], s[20:21], v35, s9, v[118:119]
	v_lshl_add_u64 v[22:23], v[22:23], 0, s[18:19]
	v_pk_mul_f32 v[28:29], v[20:21], v[28:29]
	v_lshl_add_u64 v[22:23], v[22:23], 0, s[16:17]
	v_cvt_pk_bf16_f32 v20, v26, v27
	v_cvt_pk_bf16_f32 v21, v28, v29
	v_lshl_add_u64 v[22:23], v[22:23], 0, v[0:1]
	flat_store_dwordx4 v[22:23], v[18:21]
	s_nop 0
	s_nop 0
	v_add_u32_e32 v19, 0xb0, v142
	v_fmamk_f32 v18, v166, 0x3a000000, v188
	v_cmp_gt_f32_e32 vcc, s52, v18
	v_mul_f32_e32 v20, 0x4b800000, v18
	s_nop 0
	v_cndmask_b32_e32 v18, v18, v20, vcc
	v_rsq_f32_e32 v18, v18
	s_nop 0
	v_mul_f32_e32 v20, 0x45800000, v18
	v_cndmask_b32_e32 v18, v18, v20, vcc
	v_pk_mul_f32 v[14:15], v[14:15], v[18:19] op_sel_hi:[1,0]
	v_pk_mul_f32 v[6:7], v[6:7], v[18:19] op_sel_hi:[1,0]
	v_mul_f32_e32 v20, 0xbfb8aa3b, v14
	v_pk_mul_f32 v[6:7], v[14:15], v[6:7]
	v_mul_f32_e32 v14, 0xbfb8aa3b, v15
	v_exp_f32_e32 v14, v14
	v_pk_mul_f32 v[8:9], v[8:9], v[18:19] op_sel_hi:[1,0]
	v_pk_mul_f32 v[10:11], v[10:11], v[18:19] op_sel_hi:[1,0]
	v_pk_mul_f32 v[2:3], v[2:3], v[18:19] op_sel_hi:[1,0]
	v_add_f32_e32 v14, 1.0, v14
	v_rcp_f32_e32 v21, v14
	v_pk_mul_f32 v[14:15], v[16:17], v[18:19] op_sel_hi:[1,0]
	v_pk_mul_f32 v[2:3], v[10:11], v[2:3]
	v_mul_f32_e32 v16, 0xbfb8aa3b, v14
	v_pk_mul_f32 v[8:9], v[14:15], v[8:9]
	v_mul_f32_e32 v14, 0xbfb8aa3b, v15
	v_exp_f32_e32 v14, v14
	v_exp_f32_e32 v20, v20
	v_pk_mul_f32 v[4:5], v[4:5], v[18:19] op_sel_hi:[1,0]
	v_exp_f32_e32 v16, v16
	v_add_f32_e32 v14, 1.0, v14
	v_rcp_f32_e32 v17, v14
	v_mul_f32_e32 v14, 0xbfb8aa3b, v10
	v_mul_f32_e32 v10, 0xbfb8aa3b, v11
	v_exp_f32_e32 v14, v14
	v_exp_f32_e32 v10, v10
	v_add_f32_e32 v20, 1.0, v20
	v_rcp_f32_e32 v20, v20
	v_add_f32_e32 v14, 1.0, v14
	v_add_f32_e32 v10, 1.0, v10
	v_rcp_f32_e32 v14, v14
	v_rcp_f32_e32 v15, v10
	v_add_f32_e32 v16, 1.0, v16
	v_rcp_f32_e32 v16, v16
	v_pk_mul_f32 v[6:7], v[6:7], v[20:21]
	v_pk_mul_f32 v[10:11], v[2:3], v[14:15]
	v_pk_mul_f32 v[2:3], v[12:13], v[18:19] op_sel_hi:[1,0]
	v_pk_mul_f32 v[8:9], v[8:9], v[16:17]
	v_mul_f32_e32 v12, 0xbfb8aa3b, v2
	v_pk_mul_f32 v[4:5], v[2:3], v[4:5]
	v_mul_f32_e32 v2, 0xbfb8aa3b, v3
	v_exp_f32_e32 v12, v12
	v_exp_f32_e32 v2, v2
	v_cvt_pk_bf16_f32 v3, v8, v9
	s_andn2_b64 vcc, exec, s[40:41]
	v_add_f32_e32 v12, 1.0, v12
	v_add_f32_e32 v2, 1.0, v2
	v_rcp_f32_e32 v12, v12
	v_rcp_f32_e32 v13, v2
	v_cvt_pk_bf16_f32 v2, v6, v7
	v_mad_i64_i32 v[6:7], s[20:21], v19, s9, v[118:119]
	v_lshl_add_u64 v[6:7], v[6:7], 0, s[18:19]
	v_pk_mul_f32 v[12:13], v[4:5], v[12:13]
	v_lshl_add_u64 v[6:7], v[6:7], 0, s[16:17]
	v_cvt_pk_bf16_f32 v4, v10, v11
	v_cvt_pk_bf16_f32 v5, v12, v13
	v_lshl_add_u64 v[6:7], v[6:7], 0, v[0:1]
	s_mov_b64 s[18:19], -1
	flat_store_dwordx4 v[6:7], v[2:5]
	s_cbranch_vccnz .LBB0_1236
	s_andn2_b64 vcc, exec, s[4:5]
	s_cbranch_vccnz .LBB0_1235
	s_barrier
	s_branch .LBB0_1235

;     DI void operator()(const f32x4 (&acc)[2][2][4][2], const pg8::Unit& u, int wr, int wc, int fr, int fq) const {
;     ...
;         for (int ai = 0; ai < 2; ++ai)
; #pragma unroll
;             for (int m = 0; m < 4; ++m) {
;                 const int row = u.pm * 256 + ai * 128 + wr * 64 + m * 16 + fr;
;                 float sq = 0.f;
; #pragma unroll
;                 for (int bj = 0; bj < 2; ++bj) {
;                     const size_t off = (size_t)row * DM + u.pn * 256 + bj * 128 + wc * 32 + 8 * fq;
;                     const u32x4 r = *(const u32x4*)(xb + off);
;                     f32x4 a, b;
;                     a[0] = __builtin_bit_cast(float, r.x << 16); a[1] = __builtin_bit_cast(float, r.x & 0xffff0000u); a[2] = __builtin_bit_cast(float, r.y << 16); a[3] = __builtin_bit_cast(float, r.y & 0xffff0000u);
;                     b[0] = __builtin_bit_cast(float, r.z << 16); b[1] = __builtin_bit_cast(float, r.z & 0xffff0000u); b[2] = __builtin_bit_cast(float, r.w << 16); b[3] = __builtin_bit_cast(float, r.w & 0xffff0000u);
;                     a += acc[ai][bj][m][0]; b += acc[ai][bj][m][1];
;                     if (xout) { *(f32x4*)(xout + off) = a; *(f32x4*)(xout + off + 4) = b; }
.LBB0_1327:
	s_lshl_b32 s18, s23, 8
	v_add_u32_e32 v144, s18, v137
	v_ashrrev_i32_e32 v145, 31, v144
	s_lshl_b32 s20, s22, 8
	v_lshlrev_b64 v[146:147], 11, v[144:145]
	s_ashr_i32 s21, s20, 31
	v_lshl_add_u64 v[146:147], v[146:147], 0, s[20:21]
	v_readlane_b32 s28, v254, 54
	v_or_b32_e32 v146, v146, v136
	v_readlane_b32 s29, v254, 55
	v_cndmask_b32_e64 v145, 0, 1, s[10:11]
	v_cmp_ne_u32_e64 s[2:3], 1, v145
	v_lshl_add_u64 v[150:151], v[146:147], 1, s[28:29]
	s_mov_b32 s23, 0
	global_load_dwordx4 v[172:175], v[150:151], off
	global_load_dwordx4 v[176:179], v[150:151], off offset:256
	s_mov_b32 s22, 0x10000
	v_lshl_add_u64 v[168:169], s[22:23], 0, v[150:151]
	global_load_dwordx4 v[180:183], v[168:169], off
	global_load_dwordx4 v[184:187], v[168:169], off offset:256
	s_mov_b32 s22, 0x20000
	v_lshl_add_u64 v[168:169], s[22:23], 0, v[150:151]
	global_load_dwordx4 v[196:199], v[168:169], off
	global_load_dwordx4 v[200:203], v[168:169], off offset:256
	s_mov_b32 s22, 0x30000
	v_lshl_add_u64 v[168:169], s[22:23], 0, v[150:151]
	global_load_dwordx4 v[204:207], v[168:169], off
	global_load_dwordx4 v[208:211], v[168:169], off offset:256
	s_mov_b32 s22, 0x80000
	v_lshl_add_u64 v[168:169], s[22:23], 0, v[150:151]
	global_load_dwordx4 v[212:215], v[168:169], off
	global_load_dwordx4 v[216:219], v[168:169], off offset:256
	s_mov_b32 s22, 0x90000
	v_lshl_add_u64 v[168:169], s[22:23], 0, v[150:151]
	global_load_dwordx4 v[220:223], v[168:169], off
	global_load_dwordx4 v[224:227], v[168:169], off offset:256
	s_mov_b32 s22, 0xa0000
	v_lshl_add_u64 v[168:169], s[22:23], 0, v[150:151]
	global_load_dwordx4 v[236:239], v[168:169], off
	global_load_dwordx4 v[240:243], v[168:169], off offset:256
	s_mov_b32 s22, 0xb0000
	v_lshl_add_u64 v[168:169], s[22:23], 0, v[150:151]
	global_load_dwordx4 v[244:247], v[168:169], off
	global_load_dwordx4 v[248:251], v[168:169], off offset:256
	s_waitcnt vmcnt(0)
	s_andn2_b64 vcc, exec, s[10:11]
	v_lshlrev_b32_e32 v148, 16, v172
	v_and_b32_e32 v149, 0xffff0000, v172
	v_lshlrev_b32_e32 v166, 16, v173
	v_and_b32_e32 v167, 0xffff0000, v173
	v_lshlrev_b32_e32 v170, 16, v174
	v_and_b32_e32 v171, 0xffff0000, v174
	v_lshlrev_b32_e32 v168, 16, v175
	v_and_b32_e32 v169, 0xffff0000, v175
	v_pk_add_f32 v[128:129], v[128:129], v[166:167]
	v_pk_add_f32 v[126:127], v[126:127], v[148:149]
	v_pk_add_f32 v[124:125], v[124:125], v[168:169]
	v_pk_add_f32 v[122:123], v[122:123], v[170:171]
	v_lshl_add_u64 v[148:149], v[146:147], 2, s[54:55]
	s_cbranch_vccnz .LBB0_1412
	global_store_dwordx4 v[148:149], v[126:129], off
	global_store_dwordx4 v[148:149], v[122:125], off offset:16
	s_cbranch_execnz .LBB0_1330

;     DI void operator()(const f32x4 (&acc)[2][2][4][2], const pg8::Unit& u, int wr, int wc, int fr, int fq) const {
;     ...
;                 for (int bj = 0; bj < 2; ++bj) {
;                     const size_t off = (size_t)row * DM + u.pn * 256 + bj * 128 + wc * 32 + 8 * fq;
;                     const u32x4 r = *(const u32x4*)(xb + off);
;                     f32x4 a, b;
;                     a[0] = __builtin_bit_cast(float, r.x << 16); a[1] = __builtin_bit_cast(float, r.x & 0xffff0000u); a[2] = __builtin_bit_cast(float, r.y << 16); a[3] = __builtin_bit_cast(float, r.y & 0xffff0000u);
;                     b[0] = __builtin_bit_cast(float, r.z << 16); b[1] = __builtin_bit_cast(float, r.z & 0xffff0000u); b[2] = __builtin_bit_cast(float, r.w << 16); b[3] = __builtin_bit_cast(float, r.w & 0xffff0000u);
;                     a += acc[ai][bj][m][0]; b += acc[ai][bj][m][1];
;                     if (xout) { *(f32x4*)(xout + off) = a; *(f32x4*)(xout + off + 4) = b; }
.LBB0_1330:
	v_lshlrev_b64 v[146:147], 1, v[146:147]
	v_or_b32_e32 v146, 0x100, v146
	v_lshl_add_u64 v[146:147], s[28:29], 0, v[146:147]
	s_and_b64 vcc, exec, s[2:3]
	v_lshlrev_b32_e32 v150, 16, v176
	v_and_b32_e32 v151, 0xffff0000, v176
	v_lshlrev_b32_e32 v166, 16, v177
	v_and_b32_e32 v167, 0xffff0000, v177
	v_lshlrev_b32_e32 v170, 16, v178
	v_and_b32_e32 v171, 0xffff0000, v178
	v_lshlrev_b32_e32 v168, 16, v179
	v_and_b32_e32 v169, 0xffff0000, v179
	v_pk_add_f32 v[120:121], v[120:121], v[166:167]
	v_pk_add_f32 v[118:119], v[118:119], v[150:151]
	v_pk_add_f32 v[116:117], v[116:117], v[168:169]
	v_pk_add_f32 v[114:115], v[114:115], v[170:171]
	s_cbranch_vccnz .LBB0_1413
	global_store_dwordx4 v[148:149], v[118:121], off offset:512
	global_store_dwordx4 v[148:149], v[114:117], off offset:528
	s_cbranch_execnz .LBB0_1333

;     DI void operator()(const f32x4 (&acc)[2][2][4][2], const pg8::Unit& u, int wr, int wc, int fr, int fq) const {
;     ...
;                 for (int bj = 0; bj < 2; ++bj) {
;                     const size_t off = (size_t)row * DM + u.pn * 256 + bj * 128 + wc * 32 + 8 * fq;
;                     const u32x4 r = *(const u32x4*)(xb + off);
;                     f32x4 a, b;
;                     a[0] = __builtin_bit_cast(float, r.x << 16); a[1] = __builtin_bit_cast(float, r.x & 0xffff0000u); a[2] = __builtin_bit_cast(float, r.y << 16); a[3] = __builtin_bit_cast(float, r.y & 0xffff0000u);
;                     b[0] = __builtin_bit_cast(float, r.z << 16); b[1] = __builtin_bit_cast(float, r.z & 0xffff0000u); b[2] = __builtin_bit_cast(float, r.w << 16); b[3] = __builtin_bit_cast(float, r.w & 0xffff0000u);
;                     a += acc[ai][bj][m][0]; b += acc[ai][bj][m][1];
;                     if (xout) { *(f32x4*)(xout + off) = a; *(f32x4*)(xout + off + 4) = b; }
.LBB0_1337:
	v_add_u32_e32 v114, s18, v155
	s_waitcnt lgkmcnt(0)
	v_ashrrev_i32_e32 v115, 31, v114
	v_lshlrev_b64 v[114:115], 11, v[114:115]
	v_lshl_add_u64 v[116:117], v[114:115], 0, s[20:21]
	v_or_b32_e32 v116, v116, v136
	v_lshl_add_u64 v[118:119], v[116:117], 1, s[28:29]
	s_and_b64 vcc, exec, s[2:3]
	v_lshlrev_b32_e32 v114, 16, v180
	v_and_b32_e32 v115, 0xffff0000, v180
	v_lshlrev_b32_e32 v120, 16, v181
	v_and_b32_e32 v121, 0xffff0000, v181
	v_lshlrev_b32_e32 v124, 16, v182
	v_and_b32_e32 v125, 0xffff0000, v182
	v_lshlrev_b32_e32 v122, 16, v183
	v_and_b32_e32 v123, 0xffff0000, v183
	v_pk_add_f32 v[112:113], v[112:113], v[120:121]
	v_pk_add_f32 v[110:111], v[110:111], v[114:115]
	v_pk_add_f32 v[108:109], v[108:109], v[122:123]
	v_pk_add_f32 v[106:107], v[106:107], v[124:125]
	v_lshl_add_u64 v[114:115], v[116:117], 2, s[54:55]
	s_cbranch_vccnz .LBB0_1414
	global_store_dwordx4 v[114:115], v[110:113], off
	global_store_dwordx4 v[114:115], v[106:109], off offset:16
	s_cbranch_execnz .LBB0_1340

;     DI void operator()(const f32x4 (&acc)[2][2][4][2], const pg8::Unit& u, int wr, int wc, int fr, int fq) const {
;     ...
;                 for (int bj = 0; bj < 2; ++bj) {
;                     const size_t off = (size_t)row * DM + u.pn * 256 + bj * 128 + wc * 32 + 8 * fq;
;                     const u32x4 r = *(const u32x4*)(xb + off);
;                     f32x4 a, b;
;                     a[0] = __builtin_bit_cast(float, r.x << 16); a[1] = __builtin_bit_cast(float, r.x & 0xffff0000u); a[2] = __builtin_bit_cast(float, r.y << 16); a[3] = __builtin_bit_cast(float, r.y & 0xffff0000u);
;                     b[0] = __builtin_bit_cast(float, r.z << 16); b[1] = __builtin_bit_cast(float, r.z & 0xffff0000u); b[2] = __builtin_bit_cast(float, r.w << 16); b[3] = __builtin_bit_cast(float, r.w & 0xffff0000u);
;                     a += acc[ai][bj][m][0]; b += acc[ai][bj][m][1];
;                     if (xout) { *(f32x4*)(xout + off) = a; *(f32x4*)(xout + off + 4) = b; }
.LBB0_1340:
	v_lshlrev_b64 v[116:117], 1, v[116:117]
	v_or_b32_e32 v116, 0x100, v116
	v_lshl_add_u64 v[116:117], s[28:29], 0, v[116:117]
	s_and_b64 vcc, exec, s[2:3]
	v_lshlrev_b32_e32 v122, 16, v184
	v_and_b32_e32 v123, 0xffff0000, v184
	v_lshlrev_b32_e32 v118, 16, v185
	v_and_b32_e32 v119, 0xffff0000, v185
	v_lshlrev_b32_e32 v124, 16, v186
	v_and_b32_e32 v125, 0xffff0000, v186
	v_lshlrev_b32_e32 v120, 16, v187
	v_and_b32_e32 v121, 0xffff0000, v187
	v_pk_add_f32 v[104:105], v[104:105], v[118:119]
	v_pk_add_f32 v[102:103], v[102:103], v[122:123]
	v_pk_add_f32 v[100:101], v[100:101], v[120:121]
	v_pk_add_f32 v[98:99], v[98:99], v[124:125]
	s_cbranch_vccnz .LBB0_1415
	global_store_dwordx4 v[114:115], v[102:105], off offset:512
	global_store_dwordx4 v[114:115], v[98:101], off offset:528
	s_cbranch_execnz .LBB0_1343

;     DI void operator()(const f32x4 (&acc)[2][2][4][2], const pg8::Unit& u, int wr, int wc, int fr, int fq) const {
;     ...
;                 for (int bj = 0; bj < 2; ++bj) {
;                     const size_t off = (size_t)row * DM + u.pn * 256 + bj * 128 + wc * 32 + 8 * fq;
;                     const u32x4 r = *(const u32x4*)(xb + off);
;                     f32x4 a, b;
;                     a[0] = __builtin_bit_cast(float, r.x << 16); a[1] = __builtin_bit_cast(float, r.x & 0xffff0000u); a[2] = __builtin_bit_cast(float, r.y << 16); a[3] = __builtin_bit_cast(float, r.y & 0xffff0000u);
;                     b[0] = __builtin_bit_cast(float, r.z << 16); b[1] = __builtin_bit_cast(float, r.z & 0xffff0000u); b[2] = __builtin_bit_cast(float, r.w << 16); b[3] = __builtin_bit_cast(float, r.w & 0xffff0000u);
;                     a += acc[ai][bj][m][0]; b += acc[ai][bj][m][1];
;                     if (xout) { *(f32x4*)(xout + off) = a; *(f32x4*)(xout + off + 4) = b; }
.LBB0_1347:
	v_add_u32_e32 v98, s18, v156
	s_waitcnt lgkmcnt(0)
	v_ashrrev_i32_e32 v99, 31, v98
	v_lshlrev_b64 v[98:99], 11, v[98:99]
	v_lshl_add_u64 v[100:101], v[98:99], 0, s[20:21]
	v_or_b32_e32 v100, v100, v136
	v_lshl_add_u64 v[102:103], v[100:101], 1, s[28:29]
	s_and_b64 vcc, exec, s[2:3]
	v_lshlrev_b32_e32 v98, 16, v196
	v_and_b32_e32 v99, 0xffff0000, v196
	v_lshlrev_b32_e32 v104, 16, v197
	v_and_b32_e32 v105, 0xffff0000, v197
	v_lshlrev_b32_e32 v108, 16, v198
	v_and_b32_e32 v109, 0xffff0000, v198
	v_lshlrev_b32_e32 v106, 16, v199
	v_and_b32_e32 v107, 0xffff0000, v199
	v_pk_add_f32 v[96:97], v[96:97], v[104:105]
	v_pk_add_f32 v[94:95], v[94:95], v[98:99]
	v_pk_add_f32 v[92:93], v[92:93], v[106:107]
	v_pk_add_f32 v[90:91], v[90:91], v[108:109]
	v_lshl_add_u64 v[98:99], v[100:101], 2, s[54:55]
	s_cbranch_vccnz .LBB0_1416
	global_store_dwordx4 v[98:99], v[94:97], off
	global_store_dwordx4 v[98:99], v[90:93], off offset:16
	s_cbranch_execnz .LBB0_1350

;     DI void operator()(const f32x4 (&acc)[2][2][4][2], const pg8::Unit& u, int wr, int wc, int fr, int fq) const {
;     ...
;                 for (int bj = 0; bj < 2; ++bj) {
;                     const size_t off = (size_t)row * DM + u.pn * 256 + bj * 128 + wc * 32 + 8 * fq;
;                     const u32x4 r = *(const u32x4*)(xb + off);
;                     f32x4 a, b;
;                     a[0] = __builtin_bit_cast(float, r.x << 16); a[1] = __builtin_bit_cast(float, r.x & 0xffff0000u); a[2] = __builtin_bit_cast(float, r.y << 16); a[3] = __builtin_bit_cast(float, r.y & 0xffff0000u);
;                     b[0] = __builtin_bit_cast(float, r.z << 16); b[1] = __builtin_bit_cast(float, r.z & 0xffff0000u); b[2] = __builtin_bit_cast(float, r.w << 16); b[3] = __builtin_bit_cast(float, r.w & 0xffff0000u);
;                     a += acc[ai][bj][m][0]; b += acc[ai][bj][m][1];
;                     if (xout) { *(f32x4*)(xout + off) = a; *(f32x4*)(xout + off + 4) = b; }
.LBB0_1350:
	v_lshlrev_b64 v[100:101], 1, v[100:101]
	v_or_b32_e32 v100, 0x100, v100
	v_lshl_add_u64 v[100:101], s[28:29], 0, v[100:101]
	s_and_b64 vcc, exec, s[2:3]
	v_lshlrev_b32_e32 v106, 16, v200
	v_and_b32_e32 v107, 0xffff0000, v200
	v_lshlrev_b32_e32 v102, 16, v201
	v_and_b32_e32 v103, 0xffff0000, v201
	v_lshlrev_b32_e32 v108, 16, v202
	v_and_b32_e32 v109, 0xffff0000, v202
	v_lshlrev_b32_e32 v104, 16, v203
	v_and_b32_e32 v105, 0xffff0000, v203
	v_pk_add_f32 v[88:89], v[88:89], v[102:103]
	v_pk_add_f32 v[86:87], v[86:87], v[106:107]
	v_pk_add_f32 v[84:85], v[84:85], v[104:105]
	v_pk_add_f32 v[82:83], v[82:83], v[108:109]
	s_cbranch_vccnz .LBB0_1417
	global_store_dwordx4 v[98:99], v[86:89], off offset:512
	global_store_dwordx4 v[98:99], v[82:85], off offset:528
	s_cbranch_execnz .LBB0_1353

;     DI void operator()(const f32x4 (&acc)[2][2][4][2], const pg8::Unit& u, int wr, int wc, int fr, int fq) const {
;     ...
;                 for (int bj = 0; bj < 2; ++bj) {
;                     const size_t off = (size_t)row * DM + u.pn * 256 + bj * 128 + wc * 32 + 8 * fq;
;                     const u32x4 r = *(const u32x4*)(xb + off);
;                     f32x4 a, b;
;                     a[0] = __builtin_bit_cast(float, r.x << 16); a[1] = __builtin_bit_cast(float, r.x & 0xffff0000u); a[2] = __builtin_bit_cast(float, r.y << 16); a[3] = __builtin_bit_cast(float, r.y & 0xffff0000u);
;                     b[0] = __builtin_bit_cast(float, r.z << 16); b[1] = __builtin_bit_cast(float, r.z & 0xffff0000u); b[2] = __builtin_bit_cast(float, r.w << 16); b[3] = __builtin_bit_cast(float, r.w & 0xffff0000u);
;                     a += acc[ai][bj][m][0]; b += acc[ai][bj][m][1];
;                     if (xout) { *(f32x4*)(xout + off) = a; *(f32x4*)(xout + off + 4) = b; }
.LBB0_1357:
	v_add_u32_e32 v82, s18, v157
	s_waitcnt lgkmcnt(0)
	v_ashrrev_i32_e32 v83, 31, v82
	v_lshlrev_b64 v[82:83], 11, v[82:83]
	v_lshl_add_u64 v[84:85], v[82:83], 0, s[20:21]
	v_or_b32_e32 v84, v84, v136
	v_lshl_add_u64 v[86:87], v[84:85], 1, s[28:29]
	s_and_b64 vcc, exec, s[2:3]
	v_lshlrev_b32_e32 v82, 16, v204
	v_and_b32_e32 v83, 0xffff0000, v204
	v_lshlrev_b32_e32 v88, 16, v205
	v_and_b32_e32 v89, 0xffff0000, v205
	v_lshlrev_b32_e32 v92, 16, v206
	v_and_b32_e32 v93, 0xffff0000, v206
	v_lshlrev_b32_e32 v90, 16, v207
	v_and_b32_e32 v91, 0xffff0000, v207
	v_pk_add_f32 v[80:81], v[80:81], v[88:89]
	v_pk_add_f32 v[78:79], v[78:79], v[82:83]
	v_pk_add_f32 v[76:77], v[76:77], v[90:91]
	v_pk_add_f32 v[74:75], v[74:75], v[92:93]
	v_lshl_add_u64 v[82:83], v[84:85], 2, s[54:55]
	s_cbranch_vccnz .LBB0_1418
	global_store_dwordx4 v[82:83], v[78:81], off
	global_store_dwordx4 v[82:83], v[74:77], off offset:16
	s_cbranch_execnz .LBB0_1360

;     DI void operator()(const f32x4 (&acc)[2][2][4][2], const pg8::Unit& u, int wr, int wc, int fr, int fq) const {
;     ...
;                 for (int bj = 0; bj < 2; ++bj) {
;                     const size_t off = (size_t)row * DM + u.pn * 256 + bj * 128 + wc * 32 + 8 * fq;
;                     const u32x4 r = *(const u32x4*)(xb + off);
;                     f32x4 a, b;
;                     a[0] = __builtin_bit_cast(float, r.x << 16); a[1] = __builtin_bit_cast(float, r.x & 0xffff0000u); a[2] = __builtin_bit_cast(float, r.y << 16); a[3] = __builtin_bit_cast(float, r.y & 0xffff0000u);
;                     b[0] = __builtin_bit_cast(float, r.z << 16); b[1] = __builtin_bit_cast(float, r.z & 0xffff0000u); b[2] = __builtin_bit_cast(float, r.w << 16); b[3] = __builtin_bit_cast(float, r.w & 0xffff0000u);
;                     a += acc[ai][bj][m][0]; b += acc[ai][bj][m][1];
;                     if (xout) { *(f32x4*)(xout + off) = a; *(f32x4*)(xout + off + 4) = b; }
.LBB0_1360:
	v_lshlrev_b64 v[84:85], 1, v[84:85]
	v_or_b32_e32 v84, 0x100, v84
	v_lshl_add_u64 v[84:85], s[28:29], 0, v[84:85]
	s_and_b64 vcc, exec, s[2:3]
	v_lshlrev_b32_e32 v90, 16, v208
	v_and_b32_e32 v91, 0xffff0000, v208
	v_lshlrev_b32_e32 v86, 16, v209
	v_and_b32_e32 v87, 0xffff0000, v209
	v_lshlrev_b32_e32 v92, 16, v210
	v_and_b32_e32 v93, 0xffff0000, v210
	v_lshlrev_b32_e32 v88, 16, v211
	v_and_b32_e32 v89, 0xffff0000, v211
	v_pk_add_f32 v[72:73], v[72:73], v[86:87]
	v_pk_add_f32 v[70:71], v[70:71], v[90:91]
	v_pk_add_f32 v[68:69], v[68:69], v[88:89]
	v_pk_add_f32 v[66:67], v[66:67], v[92:93]
	s_cbranch_vccnz .LBB0_1419
	global_store_dwordx4 v[82:83], v[70:73], off offset:512
	global_store_dwordx4 v[82:83], v[66:69], off offset:528
	s_cbranch_execnz .LBB0_1363

;     DI void operator()(const f32x4 (&acc)[2][2][4][2], const pg8::Unit& u, int wr, int wc, int fr, int fq) const {
;     ...
;                 for (int bj = 0; bj < 2; ++bj) {
;                     const size_t off = (size_t)row * DM + u.pn * 256 + bj * 128 + wc * 32 + 8 * fq;
;                     const u32x4 r = *(const u32x4*)(xb + off);
;                     f32x4 a, b;
;                     a[0] = __builtin_bit_cast(float, r.x << 16); a[1] = __builtin_bit_cast(float, r.x & 0xffff0000u); a[2] = __builtin_bit_cast(float, r.y << 16); a[3] = __builtin_bit_cast(float, r.y & 0xffff0000u);
;                     b[0] = __builtin_bit_cast(float, r.z << 16); b[1] = __builtin_bit_cast(float, r.z & 0xffff0000u); b[2] = __builtin_bit_cast(float, r.w << 16); b[3] = __builtin_bit_cast(float, r.w & 0xffff0000u);
;                     a += acc[ai][bj][m][0]; b += acc[ai][bj][m][1];
;                     if (xout) { *(f32x4*)(xout + off) = a; *(f32x4*)(xout + off + 4) = b; }
.LBB0_1367:
	v_add_u32_e32 v66, s18, v158
	s_waitcnt lgkmcnt(0)
	v_ashrrev_i32_e32 v67, 31, v66
	v_lshlrev_b64 v[66:67], 11, v[66:67]
	v_lshl_add_u64 v[68:69], v[66:67], 0, s[20:21]
	v_or_b32_e32 v68, v68, v136
	v_lshl_add_u64 v[70:71], v[68:69], 1, s[28:29]
	s_and_b64 vcc, exec, s[2:3]
	v_lshlrev_b32_e32 v66, 16, v212
	v_and_b32_e32 v67, 0xffff0000, v212
	v_lshlrev_b32_e32 v72, 16, v213
	v_and_b32_e32 v73, 0xffff0000, v213
	v_lshlrev_b32_e32 v76, 16, v214
	v_and_b32_e32 v77, 0xffff0000, v214
	v_lshlrev_b32_e32 v74, 16, v215
	v_and_b32_e32 v75, 0xffff0000, v215
	v_pk_add_f32 v[64:65], v[64:65], v[72:73]
	v_pk_add_f32 v[62:63], v[62:63], v[66:67]
	v_pk_add_f32 v[60:61], v[60:61], v[74:75]
	v_pk_add_f32 v[58:59], v[58:59], v[76:77]
	v_lshl_add_u64 v[66:67], v[68:69], 2, s[54:55]
	s_cbranch_vccnz .LBB0_1420
	global_store_dwordx4 v[66:67], v[62:65], off
	global_store_dwordx4 v[66:67], v[58:61], off offset:16
	s_cbranch_execnz .LBB0_1370

;     DI void operator()(const f32x4 (&acc)[2][2][4][2], const pg8::Unit& u, int wr, int wc, int fr, int fq) const {
;     ...
;                 for (int bj = 0; bj < 2; ++bj) {
;                     const size_t off = (size_t)row * DM + u.pn * 256 + bj * 128 + wc * 32 + 8 * fq;
;                     const u32x4 r = *(const u32x4*)(xb + off);
;                     f32x4 a, b;
;                     a[0] = __builtin_bit_cast(float, r.x << 16); a[1] = __builtin_bit_cast(float, r.x & 0xffff0000u); a[2] = __builtin_bit_cast(float, r.y << 16); a[3] = __builtin_bit_cast(float, r.y & 0xffff0000u);
;                     b[0] = __builtin_bit_cast(float, r.z << 16); b[1] = __builtin_bit_cast(float, r.z & 0xffff0000u); b[2] = __builtin_bit_cast(float, r.w << 16); b[3] = __builtin_bit_cast(float, r.w & 0xffff0000u);
;                     a += acc[ai][bj][m][0]; b += acc[ai][bj][m][1];
;                     if (xout) { *(f32x4*)(xout + off) = a; *(f32x4*)(xout + off + 4) = b; }
.LBB0_1370:
	v_lshlrev_b64 v[68:69], 1, v[68:69]
	v_or_b32_e32 v68, 0x100, v68
	v_lshl_add_u64 v[68:69], s[28:29], 0, v[68:69]
	s_and_b64 vcc, exec, s[2:3]
	v_lshlrev_b32_e32 v74, 16, v216
	v_and_b32_e32 v75, 0xffff0000, v216
	v_lshlrev_b32_e32 v70, 16, v217
	v_and_b32_e32 v71, 0xffff0000, v217
	v_lshlrev_b32_e32 v76, 16, v218
	v_and_b32_e32 v77, 0xffff0000, v218
	v_lshlrev_b32_e32 v72, 16, v219
	v_and_b32_e32 v73, 0xffff0000, v219
	v_pk_add_f32 v[56:57], v[56:57], v[70:71]
	v_pk_add_f32 v[54:55], v[54:55], v[74:75]
	v_pk_add_f32 v[52:53], v[52:53], v[72:73]
	v_pk_add_f32 v[50:51], v[50:51], v[76:77]
	s_cbranch_vccnz .LBB0_1421
	global_store_dwordx4 v[66:67], v[54:57], off offset:512
	global_store_dwordx4 v[66:67], v[50:53], off offset:528
	s_cbranch_execnz .LBB0_1373

;     DI void operator()(const f32x4 (&acc)[2][2][4][2], const pg8::Unit& u, int wr, int wc, int fr, int fq) const {
;     ...
;                 for (int bj = 0; bj < 2; ++bj) {
;                     const size_t off = (size_t)row * DM + u.pn * 256 + bj * 128 + wc * 32 + 8 * fq;
;                     const u32x4 r = *(const u32x4*)(xb + off);
;                     f32x4 a, b;
;                     a[0] = __builtin_bit_cast(float, r.x << 16); a[1] = __builtin_bit_cast(float, r.x & 0xffff0000u); a[2] = __builtin_bit_cast(float, r.y << 16); a[3] = __builtin_bit_cast(float, r.y & 0xffff0000u);
;                     b[0] = __builtin_bit_cast(float, r.z << 16); b[1] = __builtin_bit_cast(float, r.z & 0xffff0000u); b[2] = __builtin_bit_cast(float, r.w << 16); b[3] = __builtin_bit_cast(float, r.w & 0xffff0000u);
;                     a += acc[ai][bj][m][0]; b += acc[ai][bj][m][1];
;                     if (xout) { *(f32x4*)(xout + off) = a; *(f32x4*)(xout + off + 4) = b; }
.LBB0_1377:
	v_add_u32_e32 v50, 0x90, v144
	s_waitcnt lgkmcnt(0)
	v_ashrrev_i32_e32 v51, 31, v50
	v_lshlrev_b64 v[50:51], 11, v[50:51]
	v_lshl_add_u64 v[52:53], v[50:51], 0, s[20:21]
	v_or_b32_e32 v52, v52, v136
	v_lshl_add_u64 v[54:55], v[52:53], 1, s[28:29]
	s_and_b64 vcc, exec, s[2:3]
	v_lshlrev_b32_e32 v50, 16, v220
	v_and_b32_e32 v51, 0xffff0000, v220
	v_lshlrev_b32_e32 v56, 16, v221
	v_and_b32_e32 v57, 0xffff0000, v221
	v_lshlrev_b32_e32 v60, 16, v222
	v_and_b32_e32 v61, 0xffff0000, v222
	v_lshlrev_b32_e32 v58, 16, v223
	v_and_b32_e32 v59, 0xffff0000, v223
	v_pk_add_f32 v[48:49], v[48:49], v[56:57]
	v_pk_add_f32 v[46:47], v[46:47], v[50:51]
	v_pk_add_f32 v[44:45], v[44:45], v[58:59]
	v_pk_add_f32 v[42:43], v[42:43], v[60:61]
	v_lshl_add_u64 v[50:51], v[52:53], 2, s[54:55]
	s_cbranch_vccnz .LBB0_1422
	global_store_dwordx4 v[50:51], v[46:49], off
	global_store_dwordx4 v[50:51], v[42:45], off offset:16
	s_cbranch_execnz .LBB0_1380

;     DI void operator()(const f32x4 (&acc)[2][2][4][2], const pg8::Unit& u, int wr, int wc, int fr, int fq) const {
;     ...
;                 for (int bj = 0; bj < 2; ++bj) {
;                     const size_t off = (size_t)row * DM + u.pn * 256 + bj * 128 + wc * 32 + 8 * fq;
;                     const u32x4 r = *(const u32x4*)(xb + off);
;                     f32x4 a, b;
;                     a[0] = __builtin_bit_cast(float, r.x << 16); a[1] = __builtin_bit_cast(float, r.x & 0xffff0000u); a[2] = __builtin_bit_cast(float, r.y << 16); a[3] = __builtin_bit_cast(float, r.y & 0xffff0000u);
;                     b[0] = __builtin_bit_cast(float, r.z << 16); b[1] = __builtin_bit_cast(float, r.z & 0xffff0000u); b[2] = __builtin_bit_cast(float, r.w << 16); b[3] = __builtin_bit_cast(float, r.w & 0xffff0000u);
;                     a += acc[ai][bj][m][0]; b += acc[ai][bj][m][1];
;                     if (xout) { *(f32x4*)(xout + off) = a; *(f32x4*)(xout + off + 4) = b; }
.LBB0_1380:
	v_lshlrev_b64 v[52:53], 1, v[52:53]
	v_or_b32_e32 v52, 0x100, v52
	v_lshl_add_u64 v[52:53], s[28:29], 0, v[52:53]
	s_and_b64 vcc, exec, s[2:3]
	v_lshlrev_b32_e32 v58, 16, v224
	v_and_b32_e32 v59, 0xffff0000, v224
	v_lshlrev_b32_e32 v54, 16, v225
	v_and_b32_e32 v55, 0xffff0000, v225
	v_lshlrev_b32_e32 v60, 16, v226
	v_and_b32_e32 v61, 0xffff0000, v226
	v_lshlrev_b32_e32 v56, 16, v227
	v_and_b32_e32 v57, 0xffff0000, v227
	v_pk_add_f32 v[40:41], v[40:41], v[54:55]
	v_pk_add_f32 v[38:39], v[38:39], v[58:59]
	v_pk_add_f32 v[36:37], v[36:37], v[56:57]
	v_pk_add_f32 v[34:35], v[34:35], v[60:61]
	s_cbranch_vccnz .LBB0_1423
	global_store_dwordx4 v[50:51], v[38:41], off offset:512
	global_store_dwordx4 v[50:51], v[34:37], off offset:528
	s_cbranch_execnz .LBB0_1383

;     DI void operator()(const f32x4 (&acc)[2][2][4][2], const pg8::Unit& u, int wr, int wc, int fr, int fq) const {
;     ...
;                 for (int bj = 0; bj < 2; ++bj) {
;                     const size_t off = (size_t)row * DM + u.pn * 256 + bj * 128 + wc * 32 + 8 * fq;
;                     const u32x4 r = *(const u32x4*)(xb + off);
;                     f32x4 a, b;
;                     a[0] = __builtin_bit_cast(float, r.x << 16); a[1] = __builtin_bit_cast(float, r.x & 0xffff0000u); a[2] = __builtin_bit_cast(float, r.y << 16); a[3] = __builtin_bit_cast(float, r.y & 0xffff0000u);
;                     b[0] = __builtin_bit_cast(float, r.z << 16); b[1] = __builtin_bit_cast(float, r.z & 0xffff0000u); b[2] = __builtin_bit_cast(float, r.w << 16); b[3] = __builtin_bit_cast(float, r.w & 0xffff0000u);
;                     a += acc[ai][bj][m][0]; b += acc[ai][bj][m][1];
;                     if (xout) { *(f32x4*)(xout + off) = a; *(f32x4*)(xout + off + 4) = b; }
.LBB0_1387:
	v_add_u32_e32 v34, 0xa0, v144
	s_waitcnt lgkmcnt(0)
	v_ashrrev_i32_e32 v35, 31, v34
	v_lshlrev_b64 v[34:35], 11, v[34:35]
	v_lshl_add_u64 v[36:37], v[34:35], 0, s[20:21]
	v_or_b32_e32 v36, v36, v136
	v_lshl_add_u64 v[38:39], v[36:37], 1, s[28:29]
	s_and_b64 vcc, exec, s[2:3]
	v_lshlrev_b32_e32 v34, 16, v236
	v_and_b32_e32 v35, 0xffff0000, v236
	v_lshlrev_b32_e32 v40, 16, v237
	v_and_b32_e32 v41, 0xffff0000, v237
	v_lshlrev_b32_e32 v44, 16, v238
	v_and_b32_e32 v45, 0xffff0000, v238
	v_lshlrev_b32_e32 v42, 16, v239
	v_and_b32_e32 v43, 0xffff0000, v239
	v_pk_add_f32 v[32:33], v[32:33], v[40:41]
	v_pk_add_f32 v[30:31], v[30:31], v[34:35]
	v_pk_add_f32 v[28:29], v[28:29], v[42:43]
	v_pk_add_f32 v[26:27], v[26:27], v[44:45]
	v_lshl_add_u64 v[34:35], v[36:37], 2, s[54:55]
	s_cbranch_vccnz .LBB0_1424
	global_store_dwordx4 v[34:35], v[30:33], off
	global_store_dwordx4 v[34:35], v[26:29], off offset:16
	s_cbranch_execnz .LBB0_1390

;     DI void operator()(const f32x4 (&acc)[2][2][4][2], const pg8::Unit& u, int wr, int wc, int fr, int fq) const {
;     ...
;                 for (int bj = 0; bj < 2; ++bj) {
;                     const size_t off = (size_t)row * DM + u.pn * 256 + bj * 128 + wc * 32 + 8 * fq;
;                     const u32x4 r = *(const u32x4*)(xb + off);
;                     f32x4 a, b;
;                     a[0] = __builtin_bit_cast(float, r.x << 16); a[1] = __builtin_bit_cast(float, r.x & 0xffff0000u); a[2] = __builtin_bit_cast(float, r.y << 16); a[3] = __builtin_bit_cast(float, r.y & 0xffff0000u);
;                     b[0] = __builtin_bit_cast(float, r.z << 16); b[1] = __builtin_bit_cast(float, r.z & 0xffff0000u); b[2] = __builtin_bit_cast(float, r.w << 16); b[3] = __builtin_bit_cast(float, r.w & 0xffff0000u);
;                     a += acc[ai][bj][m][0]; b += acc[ai][bj][m][1];
;                     if (xout) { *(f32x4*)(xout + off) = a; *(f32x4*)(xout + off + 4) = b; }
.LBB0_1390:
	v_lshlrev_b64 v[36:37], 1, v[36:37]
	v_or_b32_e32 v36, 0x100, v36
	v_lshl_add_u64 v[36:37], s[28:29], 0, v[36:37]
	s_and_b64 vcc, exec, s[2:3]
	v_lshlrev_b32_e32 v42, 16, v240
	v_and_b32_e32 v43, 0xffff0000, v240
	v_lshlrev_b32_e32 v38, 16, v241
	v_and_b32_e32 v39, 0xffff0000, v241
	v_lshlrev_b32_e32 v44, 16, v242
	v_and_b32_e32 v45, 0xffff0000, v242
	v_lshlrev_b32_e32 v40, 16, v243
	v_and_b32_e32 v41, 0xffff0000, v243
	v_pk_add_f32 v[24:25], v[24:25], v[38:39]
	v_pk_add_f32 v[22:23], v[22:23], v[42:43]
	v_pk_add_f32 v[20:21], v[20:21], v[40:41]
	v_pk_add_f32 v[18:19], v[18:19], v[44:45]
	s_cbranch_vccnz .LBB0_1425
	global_store_dwordx4 v[34:35], v[22:25], off offset:512
	global_store_dwordx4 v[34:35], v[18:21], off offset:528
	s_cbranch_execnz .LBB0_1393

;     DI void operator()(const f32x4 (&acc)[2][2][4][2], const pg8::Unit& u, int wr, int wc, int fr, int fq) const {
;     ...
;                 for (int bj = 0; bj < 2; ++bj) {
;                     const size_t off = (size_t)row * DM + u.pn * 256 + bj * 128 + wc * 32 + 8 * fq;
;                     const u32x4 r = *(const u32x4*)(xb + off);
;                     f32x4 a, b;
;                     a[0] = __builtin_bit_cast(float, r.x << 16); a[1] = __builtin_bit_cast(float, r.x & 0xffff0000u); a[2] = __builtin_bit_cast(float, r.y << 16); a[3] = __builtin_bit_cast(float, r.y & 0xffff0000u);
;                     b[0] = __builtin_bit_cast(float, r.z << 16); b[1] = __builtin_bit_cast(float, r.z & 0xffff0000u); b[2] = __builtin_bit_cast(float, r.w << 16); b[3] = __builtin_bit_cast(float, r.w & 0xffff0000u);
;                     a += acc[ai][bj][m][0]; b += acc[ai][bj][m][1];
;                     if (xout) { *(f32x4*)(xout + off) = a; *(f32x4*)(xout + off + 4) = b; }
.LBB0_1397:
	v_add_u32_e32 v18, 0xb0, v144
	s_waitcnt lgkmcnt(0)
	v_ashrrev_i32_e32 v19, 31, v18
	v_lshlrev_b64 v[18:19], 11, v[18:19]
	v_lshl_add_u64 v[20:21], v[18:19], 0, s[20:21]
	v_or_b32_e32 v20, v20, v136
	v_lshl_add_u64 v[22:23], v[20:21], 1, s[28:29]
	s_and_b64 vcc, exec, s[2:3]
	v_lshlrev_b32_e32 v18, 16, v244
	v_and_b32_e32 v19, 0xffff0000, v244
	v_lshlrev_b32_e32 v24, 16, v245
	v_and_b32_e32 v25, 0xffff0000, v245
	v_lshlrev_b32_e32 v28, 16, v246
	v_and_b32_e32 v29, 0xffff0000, v246
	v_lshlrev_b32_e32 v26, 16, v247
	v_and_b32_e32 v27, 0xffff0000, v247
	v_pk_add_f32 v[16:17], v[16:17], v[24:25]
	v_pk_add_f32 v[14:15], v[14:15], v[18:19]
	v_pk_add_f32 v[12:13], v[12:13], v[26:27]
	v_pk_add_f32 v[10:11], v[10:11], v[28:29]
	v_lshl_add_u64 v[18:19], v[20:21], 2, s[54:55]
	s_cbranch_vccnz .LBB0_1426
	global_store_dwordx4 v[18:19], v[14:17], off
	global_store_dwordx4 v[18:19], v[10:13], off offset:16
	s_cbranch_execnz .LBB0_1400

;     DI void operator()(const f32x4 (&acc)[2][2][4][2], const pg8::Unit& u, int wr, int wc, int fr, int fq) const {
;     ...
;                 for (int bj = 0; bj < 2; ++bj) {
;                     const size_t off = (size_t)row * DM + u.pn * 256 + bj * 128 + wc * 32 + 8 * fq;
;                     const u32x4 r = *(const u32x4*)(xb + off);
;                     f32x4 a, b;
;                     a[0] = __builtin_bit_cast(float, r.x << 16); a[1] = __builtin_bit_cast(float, r.x & 0xffff0000u); a[2] = __builtin_bit_cast(float, r.y << 16); a[3] = __builtin_bit_cast(float, r.y & 0xffff0000u);
;                     b[0] = __builtin_bit_cast(float, r.z << 16); b[1] = __builtin_bit_cast(float, r.z & 0xffff0000u); b[2] = __builtin_bit_cast(float, r.w << 16); b[3] = __builtin_bit_cast(float, r.w & 0xffff0000u);
;                     a += acc[ai][bj][m][0]; b += acc[ai][bj][m][1];
;                     if (xout) { *(f32x4*)(xout + off) = a; *(f32x4*)(xout + off + 4) = b; }
.LBB0_1400:
	v_lshlrev_b64 v[20:21], 1, v[20:21]
	v_or_b32_e32 v20, 0x100, v20
	v_lshl_add_u64 v[20:21], s[28:29], 0, v[20:21]
	s_and_b64 vcc, exec, s[2:3]
	v_lshlrev_b32_e32 v26, 16, v248
	v_and_b32_e32 v27, 0xffff0000, v248
	v_lshlrev_b32_e32 v22, 16, v249
	v_and_b32_e32 v23, 0xffff0000, v249
	v_lshlrev_b32_e32 v28, 16, v250
	v_and_b32_e32 v29, 0xffff0000, v250
	v_lshlrev_b32_e32 v24, 16, v251
	v_and_b32_e32 v25, 0xffff0000, v251
	v_pk_add_f32 v[8:9], v[8:9], v[22:23]
	v_pk_add_f32 v[6:7], v[6:7], v[26:27]
	v_pk_add_f32 v[4:5], v[4:5], v[24:25]
	v_pk_add_f32 v[2:3], v[2:3], v[28:29]
	s_cbranch_vccnz .LBB0_1427
	global_store_dwordx4 v[18:19], v[6:9], off offset:512
	global_store_dwordx4 v[18:19], v[2:5], off offset:528
	s_cbranch_execnz .LBB0_1403
